# remove serializing vmcnt(0) between next-tile LDS-DMA issue and ds_reads in 4 GEMM K-loops
# speedup vs baseline: 1.0741x; 1.0741x over previous
.LBB0_62:
	s_and_b32 s10, s9, 0x8000
	s_xor_b32 s11, s10, 0x8000
	v_add_u32_e32 v79, s11, v72
	v_lshl_add_u64 v[80:81], v[64:65], 0, s[6:7]
	v_readfirstlane_b32 s11, v79
	v_lshl_add_u64 v[82:83], v[80:81], 0, s[28:29]
	s_mov_b32 m0, s11
	v_lshl_add_u64 v[84:85], v[66:67], 0, s[6:7]
	global_load_lds_dwordx4 v[82:83], off
	v_add_u32_e32 v82, 0x4000, v79
	v_lshl_add_u64 v[86:87], v[84:85], 0, s[28:29]
	v_readfirstlane_b32 s11, v82
	s_mov_b32 m0, s11
	v_lshl_add_u64 v[82:83], v[80:81], 0, s[12:13]
	global_load_lds_dwordx4 v[86:87], off
	v_add_u32_e32 v86, 0x1000, v79
	s_nop 0
	v_readfirstlane_b32 s11, v86
	v_add_u32_e32 v86, 0x5000, v79
	s_mov_b32 m0, s11
	v_readfirstlane_b32 s11, v86
	v_add_u32_e32 v86, 0x2000, v79
	global_load_lds_dwordx4 v[82:83], off
	v_lshl_add_u64 v[82:83], v[84:85], 0, s[12:13]
	s_mov_b32 m0, s11
	v_readfirstlane_b32 s11, v86
	v_add_u32_e32 v86, 0x6000, v79
	global_load_lds_dwordx4 v[82:83], off
	v_lshl_add_u64 v[82:83], v[80:81], 0, s[14:15]
	s_mov_b32 m0, s11
	v_readfirstlane_b32 s11, v86
	global_load_lds_dwordx4 v[82:83], off
	v_lshl_add_u64 v[82:83], v[84:85], 0, s[14:15]
	s_mov_b32 m0, s11
	v_lshl_add_u64 v[80:81], v[80:81], 0, s[16:17]
	global_load_lds_dwordx4 v[82:83], off
	v_add_u32_e32 v82, 0x3000, v79
	v_add_u32_e32 v79, 0x7000, v79
	v_readfirstlane_b32 s11, v82
	s_mov_b32 m0, s11
	v_readfirstlane_b32 s11, v79
	global_load_lds_dwordx4 v[80:81], off
	v_lshl_add_u64 v[80:81], v[84:85], 0, s[16:17]
	s_mov_b32 m0, s11
	v_or_b32_e32 v79, s10, v78
	global_load_lds_dwordx4 v[80:81], off
	v_add_u32_e32 v100, v79, v73
	v_add_u32_e32 v79, v79, v74
	ds_read_b128 v[80:83], v100
	ds_read_b128 v[84:87], v100 offset:2048
	ds_read_b128 v[88:91], v79 offset:16384
	ds_read_b128 v[92:95], v79 offset:18432
	ds_read_b128 v[96:99], v100 offset:4096
	ds_read_b128 v[100:103], v100 offset:6144
	ds_read_b128 v[104:107], v79 offset:20480
	ds_read_b128 v[108:111], v79 offset:22528
	v_or_b32_e32 v79, s10, v77
	v_add_u32_e32 v132, v79, v73
	v_add_u32_e32 v79, v79, v74
	ds_read_b128 v[112:115], v132
	ds_read_b128 v[116:119], v132 offset:2048
	ds_read_b128 v[120:123], v79 offset:16384
	ds_read_b128 v[124:127], v79 offset:18432
	ds_read_b128 v[128:131], v132 offset:4096
	ds_read_b128 v[132:135], v132 offset:6144
	ds_read_b128 v[146:149], v79 offset:20480
	ds_read_b128 v[150:153], v79 offset:22528
	s_waitcnt lgkmcnt(0)
	v_mfma_f32_16x16x32_bf16 v[60:63], v[80:83], v[88:91], v[60:63]
	v_mfma_f32_16x16x32_bf16 v[56:59], v[80:83], v[92:95], v[56:59]
	v_mfma_f32_16x16x32_bf16 v[52:55], v[80:83], v[104:107], v[52:55]
	v_mfma_f32_16x16x32_bf16 v[48:51], v[80:83], v[108:111], v[48:51]
	v_mfma_f32_16x16x32_bf16 v[44:47], v[84:87], v[88:91], v[44:47]
	v_mfma_f32_16x16x32_bf16 v[40:43], v[84:87], v[92:95], v[40:43]
	v_mfma_f32_16x16x32_bf16 v[36:39], v[84:87], v[104:107], v[36:39]
	v_mfma_f32_16x16x32_bf16 v[32:35], v[84:87], v[108:111], v[32:35]
	v_mfma_f32_16x16x32_bf16 v[28:31], v[96:99], v[88:91], v[28:31]
	v_mfma_f32_16x16x32_bf16 v[24:27], v[96:99], v[92:95], v[24:27]
	v_mfma_f32_16x16x32_bf16 v[20:23], v[96:99], v[104:107], v[20:23]
	v_mfma_f32_16x16x32_bf16 v[16:19], v[96:99], v[108:111], v[16:19]
	v_mfma_f32_16x16x32_bf16 v[12:15], v[100:103], v[88:91], v[12:15]
	v_mfma_f32_16x16x32_bf16 v[8:11], v[100:103], v[92:95], v[8:11]
	v_mfma_f32_16x16x32_bf16 v[4:7], v[100:103], v[104:107], v[4:7]
	v_mfma_f32_16x16x32_bf16 v[0:3], v[100:103], v[108:111], v[0:3]
	v_mfma_f32_16x16x32_bf16 v[60:63], v[112:115], v[120:123], v[60:63]
	v_mfma_f32_16x16x32_bf16 v[56:59], v[112:115], v[124:127], v[56:59]
	v_mfma_f32_16x16x32_bf16 v[52:55], v[112:115], v[146:149], v[52:55]
	v_mfma_f32_16x16x32_bf16 v[48:51], v[112:115], v[150:153], v[48:51]
	v_mfma_f32_16x16x32_bf16 v[44:47], v[116:119], v[120:123], v[44:47]
	v_mfma_f32_16x16x32_bf16 v[40:43], v[116:119], v[124:127], v[40:43]
	v_mfma_f32_16x16x32_bf16 v[36:39], v[116:119], v[146:149], v[36:39]
	v_mfma_f32_16x16x32_bf16 v[32:35], v[116:119], v[150:153], v[32:35]
	v_mfma_f32_16x16x32_bf16 v[28:31], v[128:131], v[120:123], v[28:31]
	v_mfma_f32_16x16x32_bf16 v[24:27], v[128:131], v[124:127], v[24:27]
	v_mfma_f32_16x16x32_bf16 v[20:23], v[128:131], v[146:149], v[20:23]
	v_mfma_f32_16x16x32_bf16 v[16:19], v[128:131], v[150:153], v[16:19]
	v_mfma_f32_16x16x32_bf16 v[12:15], v[132:135], v[120:123], v[12:15]
	v_mfma_f32_16x16x32_bf16 v[8:11], v[132:135], v[124:127], v[8:11]
	v_mfma_f32_16x16x32_bf16 v[4:7], v[132:135], v[146:149], v[4:7]
	v_mfma_f32_16x16x32_bf16 v[0:3], v[132:135], v[150:153], v[0:3]
	s_waitcnt vmcnt(0)
	s_add_u32 s6, s6, 0x80
	s_addc_u32 s7, s7, 0
	s_add_i32 s9, s9, 0x8000
	s_cmpk_eq_i32 s6, 0x1f80
	s_barrier
	s_cbranch_scc0 .LBB0_62
	v_add_u32_e32 v72, v78, v73
	v_add_u32_e32 v102, v78, v74
	ds_read_b128 v[64:67], v72 offset:32768
	ds_read_b128 v[78:81], v72 offset:34816
	ds_read_b128 v[82:85], v102 offset:49152
	ds_read_b128 v[86:89], v102 offset:51200
	ds_read_b128 v[90:93], v72 offset:36864
	ds_read_b128 v[94:97], v72 offset:38912
	ds_read_b128 v[98:101], v102 offset:53248
	ds_read_b128 v[102:105], v102 offset:55296
	v_add_u32_e32 v72, v77, v73
	v_add_u32_e32 v73, v77, v74
	ds_read_b128 v[106:109], v72 offset:32768
	ds_read_b128 v[110:113], v72 offset:34816
	ds_read_b128 v[114:117], v73 offset:49152
	ds_read_b128 v[118:121], v73 offset:51200
	ds_read_b128 v[122:125], v72 offset:36864
	ds_read_b128 v[126:129], v72 offset:38912
	ds_read_b128 v[130:133], v73 offset:53248
	ds_read_b128 v[146:149], v73 offset:55296
	s_waitcnt lgkmcnt(13)
	v_mfma_f32_16x16x32_bf16 v[60:63], v[64:67], v[82:85], v[60:63]
	s_waitcnt lgkmcnt(12)
	v_mfma_f32_16x16x32_bf16 v[56:59], v[64:67], v[86:89], v[56:59]
	s_waitcnt lgkmcnt(9)
	v_mfma_f32_16x16x32_bf16 v[52:55], v[64:67], v[98:101], v[52:55]
	s_waitcnt lgkmcnt(8)
	v_mfma_f32_16x16x32_bf16 v[48:51], v[64:67], v[102:105], v[48:51]
	v_mfma_f32_16x16x32_bf16 v[44:47], v[78:81], v[82:85], v[44:47]
	v_mfma_f32_16x16x32_bf16 v[40:43], v[78:81], v[86:89], v[40:43]
	v_mfma_f32_16x16x32_bf16 v[36:39], v[78:81], v[98:101], v[36:39]
	v_mfma_f32_16x16x32_bf16 v[32:35], v[78:81], v[102:105], v[32:35]
	v_mfma_f32_16x16x32_bf16 v[28:31], v[90:93], v[82:85], v[28:31]
	v_mfma_f32_16x16x32_bf16 v[24:27], v[90:93], v[86:89], v[24:27]
	v_mfma_f32_16x16x32_bf16 v[20:23], v[90:93], v[98:101], v[20:23]
	v_mfma_f32_16x16x32_bf16 v[16:19], v[90:93], v[102:105], v[16:19]
	v_mfma_f32_16x16x32_bf16 v[12:15], v[94:97], v[82:85], v[12:15]
	v_mfma_f32_16x16x32_bf16 v[8:11], v[94:97], v[86:89], v[8:11]
	v_mfma_f32_16x16x32_bf16 v[4:7], v[94:97], v[98:101], v[4:7]
	v_mfma_f32_16x16x32_bf16 v[0:3], v[94:97], v[102:105], v[0:3]
	s_waitcnt lgkmcnt(5)
	v_mfma_f32_16x16x32_bf16 v[78:81], v[106:109], v[114:117], v[60:63]
	s_waitcnt lgkmcnt(4)
	v_mfma_f32_16x16x32_bf16 v[56:59], v[106:109], v[118:121], v[56:59]
	s_waitcnt lgkmcnt(1)
	v_mfma_f32_16x16x32_bf16 v[52:55], v[106:109], v[130:133], v[52:55]
	s_waitcnt lgkmcnt(0)
	v_mfma_f32_16x16x32_bf16 v[48:51], v[106:109], v[146:149], v[48:51]
	v_mfma_f32_16x16x32_bf16 v[44:47], v[110:113], v[114:117], v[44:47]
	v_mfma_f32_16x16x32_bf16 v[40:43], v[110:113], v[118:121], v[40:43]
	v_mfma_f32_16x16x32_bf16 v[36:39], v[110:113], v[130:133], v[36:39]
	v_mfma_f32_16x16x32_bf16 v[32:35], v[110:113], v[146:149], v[32:35]
	v_mfma_f32_16x16x32_bf16 v[28:31], v[122:125], v[114:117], v[28:31]
	v_mfma_f32_16x16x32_bf16 v[24:27], v[122:125], v[118:121], v[24:27]
	v_mfma_f32_16x16x32_bf16 v[20:23], v[122:125], v[130:133], v[20:23]
	v_mfma_f32_16x16x32_bf16 v[16:19], v[122:125], v[146:149], v[16:19]
	v_mfma_f32_16x16x32_bf16 v[12:15], v[126:129], v[114:117], v[12:15]
	v_mfma_f32_16x16x32_bf16 v[8:11], v[126:129], v[118:121], v[8:11]
	v_mfma_f32_16x16x32_bf16 v[4:7], v[126:129], v[130:133], v[4:7]
	v_mfma_f32_16x16x32_bf16 v[0:3], v[126:129], v[146:149], v[0:3]
	v_add_u32_e32 v72, s5, v69
	v_add_u32_e32 v61, 0xfffff000, v72
	s_movk_i32 s6, 0x2400
	v_lshl_or_b32 v60, v75, 2, v72
	v_lshrrev_b32_e32 v61, 12, v61
	s_movk_i32 s9, 0xfff
	v_mul_lo_u32 v74, v68, s6
	v_add_u32_e32 v61, 1, v61
	v_cmp_lt_i32_e32 vcc, s9, v60
	v_readlane_b32 s6, v245, 34
	v_readlane_b32 s7, v245, 35
	v_cndmask_b32_e32 v136, 0, v61, vcc
	v_lshl_add_u64 v[66:67], v[136:137], 0, s[0:1]
	v_mov_b64_e32 v[64:65], s[6:7]
	s_movk_i32 s5, 0x6000
	v_mad_u64_u32 v[68:69], s[6:7], v66, s5, v[64:65]
	v_or_b32_e32 v66, 1, v60
	v_mad_i32_i24 v69, v67, s5, v69
	v_ashrrev_i32_e32 v67, 31, v66
	v_lshlrev_b64 v[84:85], 12, v[66:67]
	v_or_b32_e32 v66, 2, v60
	v_and_b32_e32 v73, 64, v71
	v_ashrrev_i32_e32 v67, 31, v66
	v_or3_b32 v62, v76, s4, v73
	v_lshlrev_b64 v[86:87], 12, v[66:67]
	v_or_b32_e32 v66, 3, v60
	v_readlane_b32 s36, v247, 57
	v_ashrrev_i32_e32 v61, 31, v60
	v_ashrrev_i32_e32 v67, 31, v66
	v_ashrrev_i32_e32 v63, 31, v62
	v_readlane_b32 s46, v246, 3
	v_readlane_b32 s47, v246, 4
	v_lshlrev_b64 v[82:83], 12, v[60:61]
	v_lshlrev_b64 v[88:89], 12, v[66:67]
	v_lshlrev_b64 v[66:67], 2, v[62:63]
	v_lshl_add_u64 v[62:63], v[62:63], 1, s[46:47]
	v_lshl_add_u64 v[82:83], v[62:63], 0, v[82:83]
	s_waitcnt vmcnt(0)
	s_barrier
	global_load_ushort v77, v[82:83], off
	v_lshl_add_u64 v[68:69], v[68:69], 0, v[66:67]
	global_load_dword v61, v[68:69], off
	v_lshl_add_u64 v[84:85], v[62:63], 0, v[84:85]
	s_movk_i32 s6, 0x240
	s_movk_i32 s36, 0x880
	v_readlane_b32 s37, v247, 58
	v_readlane_b32 s38, v247, 59
	v_readlane_b32 s39, v247, 60
	v_readlane_b32 s40, v247, 61
	v_readlane_b32 s41, v247, 62
	v_readlane_b32 s42, v247, 63
	v_readlane_b32 s43, v246, 0
	v_readlane_b32 s44, v246, 1
	v_readlane_b32 s45, v246, 2
	v_readlane_b32 s48, v246, 5
	v_readlane_b32 s49, v246, 6
	v_readlane_b32 s50, v246, 7
	v_readlane_b32 s51, v246, 8
	s_waitcnt vmcnt(1)
	v_lshlrev_b32_e32 v77, 16, v77
	v_mul_f32_e32 v77, 0x3fd744fd, v77
	s_waitcnt vmcnt(0)
	v_fmac_f32_e32 v77, v78, v61
	global_load_ushort v78, v[84:85], off
	s_waitcnt vmcnt(0)
	v_lshlrev_b32_e32 v78, 16, v78
	v_mul_f32_e32 v90, 0x3fd744fd, v78
	v_fmac_f32_e32 v90, v79, v61
	v_lshl_add_u64 v[78:79], v[62:63], 0, v[86:87]
	global_load_ushort v86, v[78:79], off
	s_waitcnt vmcnt(0)
	v_lshlrev_b32_e32 v86, 16, v86
	v_mul_f32_e32 v91, 0x3fd744fd, v86
	v_lshl_add_u64 v[86:87], v[62:63], 0, v[88:89]
	v_fmac_f32_e32 v91, v80, v61
	global_load_ushort v80, v[86:87], off
	s_waitcnt vmcnt(0)
	v_lshlrev_b32_e32 v80, 16, v80
	v_mul_f32_e32 v80, 0x3fd744fd, v80
	v_fmac_f32_e32 v80, v81, v61
	v_lshl_or_b32 v61, v76, 1, v74
	v_mad_u32_u24 v61, v75, s6, v61
	v_cvt_pk_bf16_f32 v75, v90, s0
	ds_write_b16 v61, v75 offset:144
	v_cvt_pk_bf16_f32 v75, v91, s0
	v_cvt_pk_bf16_f32 v76, v77, s0
	ds_write_b16 v61, v75 offset:288
	v_cvt_pk_bf16_f32 v75, v80, s0
	ds_write_b16 v61, v76
	ds_write_b16 v61, v75 offset:432
	global_load_dword v75, v[68:69], off offset:64
	global_load_ushort v76, v[82:83], off offset:32
	s_waitcnt vmcnt(0)
	v_lshlrev_b32_e32 v76, 16, v76
	v_mul_f32_e32 v76, 0x3fd744fd, v76
	v_fmac_f32_e32 v76, v56, v75
	global_load_ushort v56, v[84:85], off offset:32
	s_waitcnt vmcnt(0)
	v_lshlrev_b32_e32 v56, 16, v56
	v_mul_f32_e32 v56, 0x3fd744fd, v56
	v_fmac_f32_e32 v56, v57, v75
	global_load_ushort v57, v[78:79], off offset:32
	v_cvt_pk_bf16_f32 v56, v56, s0
	ds_write_b16 v61, v56 offset:176
	s_waitcnt vmcnt(0)
	v_lshlrev_b32_e32 v57, 16, v57
	v_mul_f32_e32 v57, 0x3fd744fd, v57
	v_fmac_f32_e32 v57, v58, v75
	global_load_ushort v58, v[86:87], off offset:32
	v_cvt_pk_bf16_f32 v56, v57, s0
	ds_write_b16 v61, v56 offset:320
	s_waitcnt vmcnt(0)
	v_lshlrev_b32_e32 v58, 16, v58
	v_mul_f32_e32 v58, 0x3fd744fd, v58
	v_fmac_f32_e32 v58, v59, v75
	v_cvt_pk_bf16_f32 v59, v76, s0
	v_cvt_pk_bf16_f32 v56, v58, s0
	ds_write_b16 v61, v59 offset:32
	ds_write_b16 v61, v56 offset:464
	global_load_dword v56, v[68:69], off offset:128
	global_load_ushort v57, v[82:83], off offset:64
	s_waitcnt vmcnt(0)
	v_lshlrev_b32_e32 v57, 16, v57
	v_mul_f32_e32 v57, 0x3fd744fd, v57
	v_fmac_f32_e32 v57, v52, v56
	global_load_ushort v52, v[84:85], off offset:64
	s_waitcnt vmcnt(0)
	v_lshlrev_b32_e32 v52, 16, v52
	v_mul_f32_e32 v52, 0x3fd744fd, v52
	v_fmac_f32_e32 v52, v53, v56
	global_load_ushort v53, v[78:79], off offset:64
	v_cvt_pk_bf16_f32 v52, v52, s0
	ds_write_b16 v61, v52 offset:208
	s_waitcnt vmcnt(0)
	v_lshlrev_b32_e32 v53, 16, v53
	v_mul_f32_e32 v53, 0x3fd744fd, v53
	v_fmac_f32_e32 v53, v54, v56
	global_load_ushort v54, v[86:87], off offset:64
	v_cvt_pk_bf16_f32 v52, v53, s0
	ds_write_b16 v61, v52 offset:352
	s_waitcnt vmcnt(0)
	v_lshlrev_b32_e32 v54, 16, v54
	v_mul_f32_e32 v54, 0x3fd744fd, v54
	v_fmac_f32_e32 v54, v55, v56
	v_cvt_pk_bf16_f32 v55, v57, s0
	v_cvt_pk_bf16_f32 v52, v54, s0
	ds_write_b16 v61, v55 offset:64
	ds_write_b16 v61, v52 offset:496
	global_load_dword v52, v[68:69], off offset:192
	global_load_ushort v53, v[82:83], off offset:96
	v_or_b32_e32 v54, 18, v60
	v_ashrrev_i32_e32 v55, 31, v54
	v_lshlrev_b64 v[56:57], 12, v[54:55]
	v_or_b32_e32 v54, 19, v60
	v_ashrrev_i32_e32 v55, 31, v54
	v_lshlrev_b64 v[58:59], 12, v[54:55]
	s_waitcnt vmcnt(0)
	v_lshlrev_b32_e32 v53, 16, v53
	v_mul_f32_e32 v53, 0x3fd744fd, v53
	v_fmac_f32_e32 v53, v48, v52
	global_load_ushort v48, v[84:85], off offset:96
	s_waitcnt vmcnt(0)
	v_lshlrev_b32_e32 v48, 16, v48
	v_mul_f32_e32 v48, 0x3fd744fd, v48
	v_fmac_f32_e32 v48, v49, v52
	global_load_ushort v49, v[78:79], off offset:96
	v_cvt_pk_bf16_f32 v48, v48, s0
	ds_write_b16 v61, v48 offset:240
	s_waitcnt vmcnt(0)
	v_lshlrev_b32_e32 v49, 16, v49
	v_mul_f32_e32 v49, 0x3fd744fd, v49
	v_fmac_f32_e32 v49, v50, v52
	global_load_ushort v50, v[86:87], off offset:96
	v_cvt_pk_bf16_f32 v48, v49, s0
	ds_write_b16 v61, v48 offset:384
	v_add_u32_e32 v49, 0xfffff010, v72
	v_lshrrev_b32_e32 v49, 12, v49
	v_add_u32_e32 v49, 1, v49
	s_waitcnt vmcnt(0)
	v_lshlrev_b32_e32 v50, 16, v50
	v_mul_f32_e32 v50, 0x3fd744fd, v50
	v_fmac_f32_e32 v50, v51, v52
	v_cvt_pk_bf16_f32 v48, v50, s0
	ds_write_b16 v61, v48 offset:528
	v_or_b32_e32 v48, 16, v60
	v_cmp_lt_i32_e32 vcc, s9, v48
	v_cvt_pk_bf16_f32 v51, v53, s0
	ds_write_b16 v61, v51 offset:96
	v_cndmask_b32_e32 v136, 0, v49, vcc
	v_ashrrev_i32_e32 v49, 31, v48
	v_lshl_add_u64 v[50:51], v[136:137], 0, s[0:1]
	v_lshlrev_b64 v[48:49], 12, v[48:49]
	v_mad_u64_u32 v[52:53], s[6:7], v50, s5, v[64:65]
	v_lshl_add_u64 v[54:55], v[62:63], 0, v[48:49]
	v_mad_i32_i24 v53, v51, s5, v53
	global_load_ushort v48, v[54:55], off
	v_lshl_add_u64 v[52:53], v[52:53], 0, v[66:67]
	global_load_dword v68, v[52:53], off
	v_or_b32_e32 v50, 17, v60
	v_ashrrev_i32_e32 v51, 31, v50
	v_lshlrev_b64 v[50:51], 12, v[50:51]
	s_waitcnt vmcnt(1)
	v_lshlrev_b32_e32 v48, 16, v48
	v_mul_f32_e32 v69, 0x3fd744fd, v48
	v_lshl_add_u64 v[48:49], v[62:63], 0, v[50:51]
	s_waitcnt vmcnt(0)
	v_fmac_f32_e32 v69, v44, v68
	global_load_ushort v44, v[48:49], off
	v_lshl_add_u64 v[50:51], v[62:63], 0, v[56:57]
	s_waitcnt vmcnt(0)
	v_lshlrev_b32_e32 v44, 16, v44
	v_mul_f32_e32 v75, 0x3fd744fd, v44
	global_load_ushort v44, v[50:51], off
	v_fmac_f32_e32 v75, v45, v68
	s_waitcnt vmcnt(0)
	v_lshlrev_b32_e32 v44, 16, v44
	v_mul_f32_e32 v56, 0x3fd744fd, v44
	v_lshl_add_u64 v[44:45], v[62:63], 0, v[58:59]
	v_fmac_f32_e32 v56, v46, v68
	global_load_ushort v46, v[44:45], off
	s_waitcnt vmcnt(0)
	v_lshlrev_b32_e32 v46, 16, v46
	v_mul_f32_e32 v46, 0x3fd744fd, v46
	v_fmac_f32_e32 v46, v47, v68
	v_cvt_pk_bf16_f32 v47, v69, s0
	ds_write_b16 v61, v47 offset:2304
	v_cvt_pk_bf16_f32 v47, v75, s0
	ds_write_b16 v61, v47 offset:2448
	v_cvt_pk_bf16_f32 v47, v56, s0
	v_cvt_pk_bf16_f32 v46, v46, s0
	ds_write_b16 v61, v47 offset:2592
	ds_write_b16 v61, v46 offset:2736
	global_load_dword v46, v[52:53], off offset:64
	global_load_ushort v47, v[54:55], off offset:32
	s_waitcnt vmcnt(0)
	v_lshlrev_b32_e32 v47, 16, v47
	v_mul_f32_e32 v47, 0x3fd744fd, v47
	v_fmac_f32_e32 v47, v40, v46
	global_load_ushort v40, v[48:49], off offset:32
	s_waitcnt vmcnt(0)
	v_lshlrev_b32_e32 v40, 16, v40
	v_mul_f32_e32 v40, 0x3fd744fd, v40
	v_fmac_f32_e32 v40, v41, v46
	global_load_ushort v41, v[50:51], off offset:32
	v_cvt_pk_bf16_f32 v40, v40, s0
	ds_write_b16 v61, v40 offset:2480
	s_waitcnt vmcnt(0)
	v_lshlrev_b32_e32 v41, 16, v41
	v_mul_f32_e32 v41, 0x3fd744fd, v41
	v_fmac_f32_e32 v41, v42, v46
	global_load_ushort v42, v[44:45], off offset:32
	v_cvt_pk_bf16_f32 v40, v41, s0
	ds_write_b16 v61, v40 offset:2624
	s_waitcnt vmcnt(0)
	v_lshlrev_b32_e32 v42, 16, v42
	v_mul_f32_e32 v42, 0x3fd744fd, v42
	v_fmac_f32_e32 v42, v43, v46
	v_cvt_pk_bf16_f32 v43, v47, s0
	v_cvt_pk_bf16_f32 v40, v42, s0
	ds_write_b16 v61, v43 offset:2336
	ds_write_b16 v61, v40 offset:2768
	global_load_dword v40, v[52:53], off offset:128
	global_load_ushort v41, v[54:55], off offset:64
	s_waitcnt vmcnt(0)
	v_lshlrev_b32_e32 v41, 16, v41
	v_mul_f32_e32 v41, 0x3fd744fd, v41
	v_fmac_f32_e32 v41, v36, v40
	global_load_ushort v36, v[48:49], off offset:64
	s_waitcnt vmcnt(0)
	v_lshlrev_b32_e32 v36, 16, v36
	v_mul_f32_e32 v36, 0x3fd744fd, v36
	v_fmac_f32_e32 v36, v37, v40
	global_load_ushort v37, v[50:51], off offset:64
	v_cvt_pk_bf16_f32 v36, v36, s0
	ds_write_b16 v61, v36 offset:2512
	s_waitcnt vmcnt(0)
	v_lshlrev_b32_e32 v37, 16, v37
	v_mul_f32_e32 v37, 0x3fd744fd, v37
	v_fmac_f32_e32 v37, v38, v40
	global_load_ushort v38, v[44:45], off offset:64
	v_cvt_pk_bf16_f32 v36, v37, s0
	ds_write_b16 v61, v36 offset:2656
	s_waitcnt vmcnt(0)
	v_lshlrev_b32_e32 v38, 16, v38
	v_mul_f32_e32 v38, 0x3fd744fd, v38
	v_fmac_f32_e32 v38, v39, v40
	v_cvt_pk_bf16_f32 v39, v41, s0
	v_cvt_pk_bf16_f32 v36, v38, s0
	ds_write_b16 v61, v39 offset:2368
	ds_write_b16 v61, v36 offset:2800
	global_load_dword v36, v[52:53], off offset:192
	global_load_ushort v37, v[54:55], off offset:96
	v_or_b32_e32 v38, 34, v60
	v_ashrrev_i32_e32 v39, 31, v38
	v_lshlrev_b64 v[40:41], 12, v[38:39]
	v_or_b32_e32 v38, 35, v60
	v_ashrrev_i32_e32 v39, 31, v38
	v_lshlrev_b64 v[42:43], 12, v[38:39]
	s_waitcnt vmcnt(0)
	v_lshlrev_b32_e32 v37, 16, v37
	v_mul_f32_e32 v37, 0x3fd744fd, v37
	v_fmac_f32_e32 v37, v32, v36
	global_load_ushort v32, v[48:49], off offset:96
	s_waitcnt vmcnt(0)
	v_lshlrev_b32_e32 v32, 16, v32
	v_mul_f32_e32 v32, 0x3fd744fd, v32
	v_fmac_f32_e32 v32, v33, v36
	global_load_ushort v33, v[50:51], off offset:96
	v_cvt_pk_bf16_f32 v32, v32, s0
	ds_write_b16 v61, v32 offset:2544
	s_waitcnt vmcnt(0)
	v_lshlrev_b32_e32 v33, 16, v33
	v_mul_f32_e32 v33, 0x3fd744fd, v33
	v_fmac_f32_e32 v33, v34, v36
	global_load_ushort v34, v[44:45], off offset:96
	v_cvt_pk_bf16_f32 v32, v33, s0
	ds_write_b16 v61, v32 offset:2688
	v_add_u32_e32 v33, 0xfffff020, v72
	v_lshrrev_b32_e32 v33, 12, v33
	v_add_u32_e32 v33, 1, v33
	s_waitcnt vmcnt(0)
	v_lshlrev_b32_e32 v34, 16, v34
	v_mul_f32_e32 v34, 0x3fd744fd, v34
	v_fmac_f32_e32 v34, v35, v36
	v_cvt_pk_bf16_f32 v32, v34, s0
	ds_write_b16 v61, v32 offset:2832
	v_or_b32_e32 v32, 32, v60
	v_cmp_lt_i32_e32 vcc, s9, v32
	v_cvt_pk_bf16_f32 v35, v37, s0
	ds_write_b16 v61, v35 offset:2400
	v_cndmask_b32_e32 v136, 0, v33, vcc
	v_ashrrev_i32_e32 v33, 31, v32
	v_lshl_add_u64 v[34:35], v[136:137], 0, s[0:1]
	v_lshlrev_b64 v[32:33], 12, v[32:33]
	v_mad_u64_u32 v[36:37], s[6:7], v34, s5, v[64:65]
	v_lshl_add_u64 v[38:39], v[62:63], 0, v[32:33]
	v_mad_i32_i24 v37, v35, s5, v37
	global_load_ushort v32, v[38:39], off
	v_lshl_add_u64 v[36:37], v[36:37], 0, v[66:67]
	global_load_dword v44, v[36:37], off
	v_or_b32_e32 v34, 33, v60
	v_ashrrev_i32_e32 v35, 31, v34
	v_lshlrev_b64 v[34:35], 12, v[34:35]
	s_waitcnt vmcnt(1)
	v_lshlrev_b32_e32 v32, 16, v32
	v_mul_f32_e32 v45, 0x3fd744fd, v32
	v_lshl_add_u64 v[32:33], v[62:63], 0, v[34:35]
	s_waitcnt vmcnt(0)
	v_fmac_f32_e32 v45, v28, v44
	global_load_ushort v28, v[32:33], off
	v_lshl_add_u64 v[34:35], v[62:63], 0, v[40:41]
	s_waitcnt vmcnt(0)
	v_lshlrev_b32_e32 v28, 16, v28
	v_mul_f32_e32 v46, 0x3fd744fd, v28
	global_load_ushort v28, v[34:35], off
	v_fmac_f32_e32 v46, v29, v44
	s_waitcnt vmcnt(0)
	v_lshlrev_b32_e32 v28, 16, v28
	v_mul_f32_e32 v40, 0x3fd744fd, v28
	v_lshl_add_u64 v[28:29], v[62:63], 0, v[42:43]
	v_fmac_f32_e32 v40, v30, v44
	global_load_ushort v30, v[28:29], off
	s_waitcnt vmcnt(0)
	v_lshlrev_b32_e32 v30, 16, v30
	v_mul_f32_e32 v30, 0x3fd744fd, v30
	v_fmac_f32_e32 v30, v31, v44
	v_cvt_pk_bf16_f32 v31, v45, s0
	ds_write_b16 v61, v31 offset:4608
	v_cvt_pk_bf16_f32 v31, v46, s0
	ds_write_b16 v61, v31 offset:4752
	v_cvt_pk_bf16_f32 v31, v40, s0
	v_cvt_pk_bf16_f32 v30, v30, s0
	ds_write_b16 v61, v31 offset:4896
	ds_write_b16 v61, v30 offset:5040
	global_load_dword v30, v[36:37], off offset:64
	global_load_ushort v31, v[38:39], off offset:32
	s_waitcnt vmcnt(0)
	v_lshlrev_b32_e32 v31, 16, v31
	v_mul_f32_e32 v31, 0x3fd744fd, v31
	v_fmac_f32_e32 v31, v24, v30
	global_load_ushort v24, v[32:33], off offset:32
	s_waitcnt vmcnt(0)
	v_lshlrev_b32_e32 v24, 16, v24
	v_mul_f32_e32 v24, 0x3fd744fd, v24
	v_fmac_f32_e32 v24, v25, v30
	global_load_ushort v25, v[34:35], off offset:32
	v_cvt_pk_bf16_f32 v24, v24, s0
	ds_write_b16 v61, v24 offset:4784
	s_waitcnt vmcnt(0)
	v_lshlrev_b32_e32 v25, 16, v25
	v_mul_f32_e32 v25, 0x3fd744fd, v25
	v_fmac_f32_e32 v25, v26, v30
	global_load_ushort v26, v[28:29], off offset:32
	v_cvt_pk_bf16_f32 v24, v25, s0
	ds_write_b16 v61, v24 offset:4928
	s_waitcnt vmcnt(0)
	v_lshlrev_b32_e32 v26, 16, v26
	v_mul_f32_e32 v26, 0x3fd744fd, v26
	v_fmac_f32_e32 v26, v27, v30
	v_cvt_pk_bf16_f32 v27, v31, s0
	v_cvt_pk_bf16_f32 v24, v26, s0
	ds_write_b16 v61, v27 offset:4640
	ds_write_b16 v61, v24 offset:5072
	global_load_dword v24, v[36:37], off offset:128
	global_load_ushort v25, v[38:39], off offset:64
	s_waitcnt vmcnt(0)
	v_lshlrev_b32_e32 v25, 16, v25
	v_mul_f32_e32 v25, 0x3fd744fd, v25
	v_fmac_f32_e32 v25, v20, v24
	global_load_ushort v20, v[32:33], off offset:64
	s_waitcnt vmcnt(0)
	v_lshlrev_b32_e32 v20, 16, v20
	v_mul_f32_e32 v20, 0x3fd744fd, v20
	v_fmac_f32_e32 v20, v21, v24
	global_load_ushort v21, v[34:35], off offset:64
	v_cvt_pk_bf16_f32 v20, v20, s0
	ds_write_b16 v61, v20 offset:4816
	s_waitcnt vmcnt(0)
	v_lshlrev_b32_e32 v21, 16, v21
	v_mul_f32_e32 v21, 0x3fd744fd, v21
	v_fmac_f32_e32 v21, v22, v24
	global_load_ushort v22, v[28:29], off offset:64
	v_cvt_pk_bf16_f32 v20, v21, s0
	ds_write_b16 v61, v20 offset:4960
	s_waitcnt vmcnt(0)
	v_lshlrev_b32_e32 v22, 16, v22
	v_mul_f32_e32 v22, 0x3fd744fd, v22
	v_fmac_f32_e32 v22, v23, v24
	v_cvt_pk_bf16_f32 v23, v25, s0
	v_cvt_pk_bf16_f32 v20, v22, s0
	ds_write_b16 v61, v23 offset:4672
	ds_write_b16 v61, v20 offset:5104
	global_load_dword v20, v[36:37], off offset:192
	global_load_ushort v21, v[38:39], off offset:96
	v_or_b32_e32 v22, 50, v60
	v_ashrrev_i32_e32 v23, 31, v22
	v_lshlrev_b64 v[24:25], 12, v[22:23]
	v_or_b32_e32 v22, 51, v60
	v_ashrrev_i32_e32 v23, 31, v22
	v_lshlrev_b64 v[26:27], 12, v[22:23]
	s_waitcnt vmcnt(0)
	v_lshlrev_b32_e32 v21, 16, v21
	v_mul_f32_e32 v21, 0x3fd744fd, v21
	v_fmac_f32_e32 v21, v16, v20
	global_load_ushort v16, v[32:33], off offset:96
	s_waitcnt vmcnt(0)
	v_lshlrev_b32_e32 v16, 16, v16
	v_mul_f32_e32 v16, 0x3fd744fd, v16
	v_fmac_f32_e32 v16, v17, v20
	global_load_ushort v17, v[34:35], off offset:96
	v_cvt_pk_bf16_f32 v16, v16, s0
	ds_write_b16 v61, v16 offset:4848
	s_waitcnt vmcnt(0)
	v_lshlrev_b32_e32 v17, 16, v17
	v_mul_f32_e32 v17, 0x3fd744fd, v17
	v_fmac_f32_e32 v17, v18, v20
	global_load_ushort v18, v[28:29], off offset:96
	v_cvt_pk_bf16_f32 v16, v17, s0
	ds_write_b16 v61, v16 offset:4992
	v_add_u32_e32 v17, 0xfffff030, v72
	v_lshrrev_b32_e32 v17, 12, v17
	v_add_u32_e32 v17, 1, v17
	s_waitcnt vmcnt(0)
	v_lshlrev_b32_e32 v18, 16, v18
	v_mul_f32_e32 v18, 0x3fd744fd, v18
	v_fmac_f32_e32 v18, v19, v20
	v_cvt_pk_bf16_f32 v16, v18, s0
	ds_write_b16 v61, v16 offset:5136
	v_or_b32_e32 v16, 48, v60
	v_cmp_lt_i32_e32 vcc, s9, v16
	v_cvt_pk_bf16_f32 v19, v21, s0
	ds_write_b16 v61, v19 offset:4704
	v_cndmask_b32_e32 v136, 0, v17, vcc
	v_ashrrev_i32_e32 v17, 31, v16
	v_lshl_add_u64 v[18:19], v[136:137], 0, s[0:1]
	v_lshlrev_b64 v[16:17], 12, v[16:17]
	v_mad_u64_u32 v[20:21], s[6:7], v18, s5, v[64:65]
	v_lshl_add_u64 v[22:23], v[62:63], 0, v[16:17]
	v_mad_i32_i24 v21, v19, s5, v21
	global_load_ushort v16, v[22:23], off
	v_lshl_add_u64 v[20:21], v[20:21], 0, v[66:67]
	global_load_dword v28, v[20:21], off
	v_or_b32_e32 v18, 49, v60
	v_ashrrev_i32_e32 v19, 31, v18
	v_lshlrev_b64 v[18:19], 12, v[18:19]
	s_ashr_i32 s5, s4, 31
	s_lshl_b64 s[4:5], s[4:5], 1
	s_add_u32 s4, s46, s4
	s_addc_u32 s5, s47, s5
	v_lshlrev_b32_e32 v136, 1, v73
	s_add_i32 s8, s8, 1
	s_mov_b64 s[6:7], 0
	s_waitcnt vmcnt(1)
	v_lshlrev_b32_e32 v16, 16, v16
	v_mul_f32_e32 v29, 0x3fd744fd, v16
	v_lshl_add_u64 v[16:17], v[62:63], 0, v[18:19]
	s_waitcnt vmcnt(0)
	v_fmac_f32_e32 v29, v12, v28
	global_load_ushort v12, v[16:17], off
	v_lshl_add_u64 v[18:19], v[62:63], 0, v[24:25]
	s_waitcnt vmcnt(0)
	v_lshlrev_b32_e32 v12, 16, v12
	v_mul_f32_e32 v30, 0x3fd744fd, v12
	global_load_ushort v12, v[18:19], off
	v_fmac_f32_e32 v30, v13, v28
	s_waitcnt vmcnt(0)
	v_lshlrev_b32_e32 v12, 16, v12
	v_mul_f32_e32 v24, 0x3fd744fd, v12
	v_lshl_add_u64 v[12:13], v[62:63], 0, v[26:27]
	v_fmac_f32_e32 v24, v14, v28
	global_load_ushort v14, v[12:13], off
	s_waitcnt vmcnt(0)
	v_lshlrev_b32_e32 v14, 16, v14
	v_mul_f32_e32 v14, 0x3fd744fd, v14
	v_fmac_f32_e32 v14, v15, v28
	v_cvt_pk_bf16_f32 v15, v29, s0
	ds_write_b16 v61, v15 offset:6912
	v_cvt_pk_bf16_f32 v15, v30, s0
	ds_write_b16 v61, v15 offset:7056
	v_cvt_pk_bf16_f32 v15, v24, s0
	v_cvt_pk_bf16_f32 v14, v14, s0
	ds_write_b16 v61, v15 offset:7200
	ds_write_b16 v61, v14 offset:7344
	global_load_dword v14, v[20:21], off offset:64
	global_load_ushort v15, v[22:23], off offset:32
	s_waitcnt vmcnt(0)
	v_lshlrev_b32_e32 v15, 16, v15
	v_mul_f32_e32 v15, 0x3fd744fd, v15
	v_fmac_f32_e32 v15, v8, v14
	global_load_ushort v8, v[16:17], off offset:32
	s_waitcnt vmcnt(0)
	v_lshlrev_b32_e32 v8, 16, v8
	v_mul_f32_e32 v8, 0x3fd744fd, v8
	v_fmac_f32_e32 v8, v9, v14
	global_load_ushort v9, v[18:19], off offset:32
	v_cvt_pk_bf16_f32 v8, v8, s0
	ds_write_b16 v61, v8 offset:7088
	s_waitcnt vmcnt(0)
	v_lshlrev_b32_e32 v9, 16, v9
	v_mul_f32_e32 v9, 0x3fd744fd, v9
	v_fmac_f32_e32 v9, v10, v14
	global_load_ushort v10, v[12:13], off offset:32
	v_cvt_pk_bf16_f32 v8, v9, s0
	ds_write_b16 v61, v8 offset:7232
	s_waitcnt vmcnt(0)
	v_lshlrev_b32_e32 v10, 16, v10
	v_mul_f32_e32 v10, 0x3fd744fd, v10
	v_fmac_f32_e32 v10, v11, v14
	v_cvt_pk_bf16_f32 v11, v15, s0
	v_cvt_pk_bf16_f32 v8, v10, s0
	ds_write_b16 v61, v11 offset:6944
	ds_write_b16 v61, v8 offset:7376
	global_load_dword v8, v[20:21], off offset:128
	global_load_ushort v9, v[22:23], off offset:64
	s_waitcnt vmcnt(0)
	v_lshlrev_b32_e32 v9, 16, v9
	v_mul_f32_e32 v9, 0x3fd744fd, v9
	v_fmac_f32_e32 v9, v4, v8
	global_load_ushort v4, v[16:17], off offset:64
	s_waitcnt vmcnt(0)
	v_lshlrev_b32_e32 v4, 16, v4
	v_mul_f32_e32 v4, 0x3fd744fd, v4
	v_fmac_f32_e32 v4, v5, v8
	global_load_ushort v5, v[18:19], off offset:64
	v_cvt_pk_bf16_f32 v4, v4, s0
	ds_write_b16 v61, v4 offset:7120
	s_waitcnt vmcnt(0)
	v_lshlrev_b32_e32 v5, 16, v5
	v_mul_f32_e32 v5, 0x3fd744fd, v5
	v_fmac_f32_e32 v5, v6, v8
	global_load_ushort v6, v[12:13], off offset:64
	v_cvt_pk_bf16_f32 v4, v5, s0
	ds_write_b16 v61, v4 offset:7264
	s_waitcnt vmcnt(0)
	v_lshlrev_b32_e32 v6, 16, v6
	v_mul_f32_e32 v6, 0x3fd744fd, v6
	v_fmac_f32_e32 v6, v7, v8
	v_cvt_pk_bf16_f32 v7, v9, s0
	v_cvt_pk_bf16_f32 v4, v6, s0
	ds_write_b16 v61, v7 offset:6976
	ds_write_b16 v61, v4 offset:7408
	global_load_dword v4, v[20:21], off offset:192
	global_load_ushort v5, v[22:23], off offset:96
	s_waitcnt vmcnt(0)
	v_lshlrev_b32_e32 v5, 16, v5
	v_mul_f32_e32 v5, 0x3fd744fd, v5
	v_fmac_f32_e32 v5, v0, v4
	global_load_ushort v0, v[16:17], off offset:96
	s_waitcnt vmcnt(0)
	v_lshlrev_b32_e32 v0, 16, v0
	v_mul_f32_e32 v0, 0x3fd744fd, v0
	v_fmac_f32_e32 v0, v1, v4
	global_load_ushort v1, v[18:19], off offset:96
	v_cvt_pk_bf16_f32 v0, v0, s0
	ds_write_b16 v61, v0 offset:7152
	s_waitcnt vmcnt(0)
	v_lshlrev_b32_e32 v1, 16, v1
	v_mul_f32_e32 v1, 0x3fd744fd, v1
	v_fmac_f32_e32 v1, v2, v4
	global_load_ushort v2, v[12:13], off offset:96
	v_cvt_pk_bf16_f32 v0, v1, s0
	ds_write_b16 v61, v0 offset:7296
	v_mov_b32_e32 v1, v137
	s_waitcnt vmcnt(0)
	v_lshlrev_b32_e32 v2, 16, v2
	v_mul_f32_e32 v2, 0x3fd744fd, v2
	v_fmac_f32_e32 v2, v3, v4
	v_cvt_pk_bf16_f32 v0, v2, s0
	ds_write_b16 v61, v0 offset:7440
	v_lshlrev_b32_e32 v0, 4, v71
	v_cvt_pk_bf16_f32 v3, v5, s0
	v_and_b32_e32 v0, 0x70, v0
	ds_write_b16 v61, v3 offset:7008
	v_or_b32_e32 v6, v74, v0
	v_lshl_add_u64 v[2:3], s[4:5], 0, v[136:137]
	s_movk_i32 s4, 0x90
	v_mad_u32_u24 v10, v70, s4, v6
	v_lshl_add_u64 v[4:5], v[2:3], 0, v[0:1]
	ds_read_b128 v[0:3], v10
	v_or_b32_e32 v6, v72, v70
	v_ashrrev_i32_e32 v7, 31, v6
	v_lshlrev_b64 v[8:9], 12, v[6:7]
	v_lshl_add_u64 v[8:9], v[4:5], 0, v[8:9]
	s_waitcnt lgkmcnt(0)
	global_store_dwordx4 v[8:9], v[0:3], off offset:2048
	ds_read_b128 v[0:3], v10 offset:1152
	v_or_b32_e32 v8, 8, v6
	v_ashrrev_i32_e32 v9, 31, v8
	v_lshlrev_b64 v[8:9], 12, v[8:9]
	v_lshl_add_u64 v[8:9], v[4:5], 0, v[8:9]
	s_waitcnt lgkmcnt(0)
	global_store_dwordx4 v[8:9], v[0:3], off offset:2048
	ds_read_b128 v[0:3], v10 offset:2304
	v_or_b32_e32 v8, 16, v6
	v_ashrrev_i32_e32 v9, 31, v8
	v_lshlrev_b64 v[8:9], 12, v[8:9]
	v_lshl_add_u64 v[8:9], v[4:5], 0, v[8:9]
	s_waitcnt lgkmcnt(0)
	global_store_dwordx4 v[8:9], v[0:3], off offset:2048
	ds_read_b128 v[0:3], v10 offset:3456
	v_or_b32_e32 v8, 24, v6
	v_ashrrev_i32_e32 v9, 31, v8
	v_lshlrev_b64 v[8:9], 12, v[8:9]
	v_lshl_add_u64 v[8:9], v[4:5], 0, v[8:9]
	s_waitcnt lgkmcnt(0)
	global_store_dwordx4 v[8:9], v[0:3], off offset:2048
	ds_read_b128 v[0:3], v10 offset:4608
	v_or_b32_e32 v8, 32, v6
	v_ashrrev_i32_e32 v9, 31, v8
	v_lshlrev_b64 v[8:9], 12, v[8:9]
	v_lshl_add_u64 v[8:9], v[4:5], 0, v[8:9]
	s_waitcnt lgkmcnt(0)
	global_store_dwordx4 v[8:9], v[0:3], off offset:2048
	ds_read_b128 v[0:3], v10 offset:5760
	v_or_b32_e32 v8, 40, v6
	v_ashrrev_i32_e32 v9, 31, v8
	v_lshlrev_b64 v[8:9], 12, v[8:9]
	v_lshl_add_u64 v[8:9], v[4:5], 0, v[8:9]
	s_waitcnt lgkmcnt(0)
	global_store_dwordx4 v[8:9], v[0:3], off offset:2048
	ds_read_b128 v[0:3], v10 offset:6912
	v_or_b32_e32 v8, 48, v6
	v_ashrrev_i32_e32 v9, 31, v8
	v_lshlrev_b64 v[8:9], 12, v[8:9]
	v_lshl_add_u64 v[8:9], v[4:5], 0, v[8:9]
	s_waitcnt lgkmcnt(0)
	global_store_dwordx4 v[8:9], v[0:3], off offset:2048
	ds_read_b128 v[0:3], v10 offset:8064
	v_or_b32_e32 v6, 56, v6
	v_ashrrev_i32_e32 v7, 31, v6
	v_lshlrev_b64 v[6:7], 12, v[6:7]
	v_lshl_add_u64 v[4:5], v[4:5], 0, v[6:7]
	s_waitcnt lgkmcnt(0)
	global_store_dwordx4 v[4:5], v[0:3], off offset:2048
	s_barrier
	s_branch .LBB0_52

.LBB0_151:
	s_and_b32 s8, s7, 0x8000
	s_xor_b32 s9, s8, 0x8000
	v_add_u32_e32 v79, s9, v74
	v_lshl_add_u64 v[80:81], v[64:65], 0, s[4:5]
	v_readfirstlane_b32 s9, v79
	v_lshl_add_u64 v[82:83], v[80:81], 0, s[28:29]
	s_mov_b32 m0, s9
	v_lshl_add_u64 v[84:85], v[66:67], 0, s[4:5]
	global_load_lds_dwordx4 v[82:83], off
	v_add_u32_e32 v82, 0x4000, v79
	v_lshl_add_u64 v[86:87], v[84:85], 0, s[28:29]
	v_readfirstlane_b32 s9, v82
	s_mov_b32 m0, s9
	v_lshl_add_u64 v[82:83], v[80:81], 0, s[10:11]
	global_load_lds_dwordx4 v[86:87], off
	v_add_u32_e32 v86, 0x1000, v79
	s_nop 0
	v_readfirstlane_b32 s9, v86
	v_add_u32_e32 v86, 0x5000, v79
	s_mov_b32 m0, s9
	v_readfirstlane_b32 s9, v86
	v_add_u32_e32 v86, 0x2000, v79
	global_load_lds_dwordx4 v[82:83], off
	v_lshl_add_u64 v[82:83], v[84:85], 0, s[10:11]
	s_mov_b32 m0, s9
	v_readfirstlane_b32 s9, v86
	v_add_u32_e32 v86, 0x6000, v79
	global_load_lds_dwordx4 v[82:83], off
	v_lshl_add_u64 v[82:83], v[80:81], 0, s[14:15]
	s_mov_b32 m0, s9
	v_readfirstlane_b32 s9, v86
	global_load_lds_dwordx4 v[82:83], off
	v_lshl_add_u64 v[82:83], v[84:85], 0, s[14:15]
	s_mov_b32 m0, s9
	v_lshl_add_u64 v[80:81], v[80:81], 0, s[12:13]
	global_load_lds_dwordx4 v[82:83], off
	v_add_u32_e32 v82, 0x3000, v79
	v_add_u32_e32 v79, 0x7000, v79
	v_readfirstlane_b32 s9, v82
	s_mov_b32 m0, s9
	v_readfirstlane_b32 s9, v79
	global_load_lds_dwordx4 v[80:81], off
	v_lshl_add_u64 v[80:81], v[84:85], 0, s[12:13]
	s_mov_b32 m0, s9
	v_or_b32_e32 v79, s8, v76
	global_load_lds_dwordx4 v[80:81], off
	v_add_u32_e32 v100, v79, v75
	v_add_u32_e32 v79, v79, v77
	ds_read_b128 v[80:83], v100
	ds_read_b128 v[84:87], v100 offset:2048
	ds_read_b128 v[88:91], v79 offset:16384
	ds_read_b128 v[92:95], v79 offset:18432
	ds_read_b128 v[96:99], v100 offset:4096
	ds_read_b128 v[100:103], v100 offset:6144
	ds_read_b128 v[104:107], v79 offset:20480
	ds_read_b128 v[108:111], v79 offset:22528
	v_or_b32_e32 v79, s8, v78
	v_add_u32_e32 v132, v79, v75
	v_add_u32_e32 v79, v79, v77
	ds_read_b128 v[112:115], v132
	ds_read_b128 v[116:119], v132 offset:2048
	ds_read_b128 v[120:123], v79 offset:16384
	ds_read_b128 v[124:127], v79 offset:18432
	ds_read_b128 v[128:131], v132 offset:4096
	ds_read_b128 v[132:135], v132 offset:6144
	ds_read_b128 v[146:149], v79 offset:20480
	ds_read_b128 v[150:153], v79 offset:22528
	s_waitcnt lgkmcnt(0)
	v_mfma_f32_16x16x32_bf16 v[60:63], v[80:83], v[88:91], v[60:63]
	v_mfma_f32_16x16x32_bf16 v[56:59], v[80:83], v[92:95], v[56:59]
	v_mfma_f32_16x16x32_bf16 v[52:55], v[80:83], v[104:107], v[52:55]
	v_mfma_f32_16x16x32_bf16 v[48:51], v[80:83], v[108:111], v[48:51]
	v_mfma_f32_16x16x32_bf16 v[44:47], v[84:87], v[88:91], v[44:47]
	v_mfma_f32_16x16x32_bf16 v[40:43], v[84:87], v[92:95], v[40:43]
	v_mfma_f32_16x16x32_bf16 v[36:39], v[84:87], v[104:107], v[36:39]
	v_mfma_f32_16x16x32_bf16 v[32:35], v[84:87], v[108:111], v[32:35]
	v_mfma_f32_16x16x32_bf16 v[28:31], v[96:99], v[88:91], v[28:31]
	v_mfma_f32_16x16x32_bf16 v[24:27], v[96:99], v[92:95], v[24:27]
	v_mfma_f32_16x16x32_bf16 v[20:23], v[96:99], v[104:107], v[20:23]
	v_mfma_f32_16x16x32_bf16 v[16:19], v[96:99], v[108:111], v[16:19]
	v_mfma_f32_16x16x32_bf16 v[12:15], v[100:103], v[88:91], v[12:15]
	v_mfma_f32_16x16x32_bf16 v[8:11], v[100:103], v[92:95], v[8:11]
	v_mfma_f32_16x16x32_bf16 v[4:7], v[100:103], v[104:107], v[4:7]
	v_mfma_f32_16x16x32_bf16 v[0:3], v[100:103], v[108:111], v[0:3]
	v_mfma_f32_16x16x32_bf16 v[60:63], v[112:115], v[120:123], v[60:63]
	v_mfma_f32_16x16x32_bf16 v[56:59], v[112:115], v[124:127], v[56:59]
	v_mfma_f32_16x16x32_bf16 v[52:55], v[112:115], v[146:149], v[52:55]
	v_mfma_f32_16x16x32_bf16 v[48:51], v[112:115], v[150:153], v[48:51]
	v_mfma_f32_16x16x32_bf16 v[44:47], v[116:119], v[120:123], v[44:47]
	v_mfma_f32_16x16x32_bf16 v[40:43], v[116:119], v[124:127], v[40:43]
	v_mfma_f32_16x16x32_bf16 v[36:39], v[116:119], v[146:149], v[36:39]
	v_mfma_f32_16x16x32_bf16 v[32:35], v[116:119], v[150:153], v[32:35]
	v_mfma_f32_16x16x32_bf16 v[28:31], v[128:131], v[120:123], v[28:31]
	v_mfma_f32_16x16x32_bf16 v[24:27], v[128:131], v[124:127], v[24:27]
	v_mfma_f32_16x16x32_bf16 v[20:23], v[128:131], v[146:149], v[20:23]
	v_mfma_f32_16x16x32_bf16 v[16:19], v[128:131], v[150:153], v[16:19]
	v_mfma_f32_16x16x32_bf16 v[12:15], v[132:135], v[120:123], v[12:15]
	v_mfma_f32_16x16x32_bf16 v[8:11], v[132:135], v[124:127], v[8:11]
	v_mfma_f32_16x16x32_bf16 v[4:7], v[132:135], v[146:149], v[4:7]
	v_mfma_f32_16x16x32_bf16 v[0:3], v[132:135], v[150:153], v[0:3]
	s_add_i32 s7, s7, 0x8000
	s_waitcnt vmcnt(0)
	s_add_u32 s4, s4, 0x80
	s_addc_u32 s5, s5, 0
	s_cmpk_lg_i32 s4, 0x780
	s_barrier
	s_cbranch_scc1 .LBB0_151
	v_add_u32_e32 v74, v78, v77
	v_add_u32_e32 v102, v78, v75
	v_add_u32_e32 v122, v76, v77
	v_add_u32_e32 v130, v76, v75
	ds_read_b128 v[64:67], v74 offset:55296
	ds_read_b128 v[78:81], v74 offset:53248
	ds_read_b128 v[82:85], v102 offset:38912
	ds_read_b128 v[86:89], v102 offset:36864
	ds_read_b128 v[90:93], v74 offset:51200
	ds_read_b128 v[94:97], v74 offset:49152
	ds_read_b128 v[98:101], v102 offset:34816
	ds_read_b128 v[102:105], v102 offset:32768
	ds_read_b128 v[74:77], v122 offset:55296
	ds_read_b128 v[106:109], v122 offset:53248
	ds_read_b128 v[110:113], v130 offset:38912
	ds_read_b128 v[114:117], v130 offset:36864
	ds_read_b128 v[118:121], v122 offset:51200
	ds_read_b128 v[122:125], v122 offset:49152
	ds_read_b128 v[126:129], v130 offset:34816
	ds_read_b128 v[130:133], v130 offset:32768
	v_and_b32_e32 v134, 64, v69
	s_waitcnt lgkmcnt(0)
	v_mfma_f32_16x16x32_bf16 v[60:63], v[130:133], v[122:125], v[60:63]
	v_mfma_f32_16x16x32_bf16 v[56:59], v[130:133], v[118:121], v[56:59]
	v_mfma_f32_16x16x32_bf16 v[52:55], v[130:133], v[106:109], v[52:55]
	v_mfma_f32_16x16x32_bf16 v[48:51], v[130:133], v[74:77], v[48:51]
	v_mfma_f32_16x16x32_bf16 v[44:47], v[126:129], v[122:125], v[44:47]
	v_mfma_f32_16x16x32_bf16 v[40:43], v[126:129], v[118:121], v[40:43]
	v_mfma_f32_16x16x32_bf16 v[36:39], v[126:129], v[106:109], v[36:39]
	v_mfma_f32_16x16x32_bf16 v[32:35], v[126:129], v[74:77], v[32:35]
	v_mfma_f32_16x16x32_bf16 v[28:31], v[114:117], v[122:125], v[28:31]
	v_mfma_f32_16x16x32_bf16 v[24:27], v[114:117], v[118:121], v[24:27]
	v_mfma_f32_16x16x32_bf16 v[20:23], v[114:117], v[106:109], v[20:23]
	v_mfma_f32_16x16x32_bf16 v[16:19], v[114:117], v[74:77], v[16:19]
	v_mfma_f32_16x16x32_bf16 v[12:15], v[110:113], v[122:125], v[12:15]
	v_mfma_f32_16x16x32_bf16 v[8:11], v[110:113], v[118:121], v[8:11]
	v_mfma_f32_16x16x32_bf16 v[4:7], v[110:113], v[106:109], v[4:7]
	v_mfma_f32_16x16x32_bf16 v[0:3], v[110:113], v[74:77], v[0:3]
	v_mfma_f32_16x16x32_bf16 v[60:63], v[102:105], v[94:97], v[60:63]
	v_mfma_f32_16x16x32_bf16 v[56:59], v[102:105], v[90:93], v[56:59]
	v_mfma_f32_16x16x32_bf16 v[52:55], v[102:105], v[78:81], v[52:55]
	v_mfma_f32_16x16x32_bf16 v[48:51], v[102:105], v[64:67], v[48:51]
	v_mfma_f32_16x16x32_bf16 v[44:47], v[98:101], v[94:97], v[44:47]
	v_mfma_f32_16x16x32_bf16 v[40:43], v[98:101], v[90:93], v[40:43]
	v_mfma_f32_16x16x32_bf16 v[36:39], v[98:101], v[78:81], v[36:39]
	v_mfma_f32_16x16x32_bf16 v[32:35], v[98:101], v[64:67], v[32:35]
	v_mfma_f32_16x16x32_bf16 v[28:31], v[86:89], v[94:97], v[28:31]
	v_mfma_f32_16x16x32_bf16 v[24:27], v[86:89], v[90:93], v[24:27]
	v_mfma_f32_16x16x32_bf16 v[20:23], v[86:89], v[78:81], v[20:23]
	v_mfma_f32_16x16x32_bf16 v[16:19], v[86:89], v[64:67], v[16:19]
	v_mfma_f32_16x16x32_bf16 v[12:15], v[82:85], v[94:97], v[12:15]
	v_mfma_f32_16x16x32_bf16 v[8:11], v[82:85], v[90:93], v[8:11]
	v_mfma_f32_16x16x32_bf16 v[4:7], v[82:85], v[78:81], v[4:7]
	v_mfma_f32_16x16x32_bf16 v[0:3], v[82:85], v[64:67], v[0:3]
	s_movk_i32 s4, 0x2400
	v_max_f32_e32 v60, v60, v60
	v_max_f32_e32 v56, v56, v56
	v_max_f32_e32 v52, v52, v52
	v_max_f32_e32 v48, v48, v48
	v_max_f32_e32 v44, v44, v44
	v_max_f32_e32 v40, v40, v40
	v_max_f32_e32 v36, v36, v36
	v_max_f32_e32 v32, v32, v32
	v_max_f32_e32 v28, v28, v28
	v_max_f32_e32 v24, v24, v24
	v_max_f32_e32 v20, v20, v20
	v_max_f32_e32 v16, v16, v16
	v_max_f32_e32 v12, v12, v12
	v_max_f32_e32 v8, v8, v8
	v_max_f32_e32 v4, v4, v4
	v_max_f32_e32 v0, v0, v0
	v_mul_lo_u32 v64, v72, s4
	v_max_f32_e32 v60, 0, v60
	v_max_f32_e32 v61, v61, v61
	v_max_f32_e32 v56, 0, v56
	v_max_f32_e32 v57, v57, v57
	v_max_f32_e32 v52, 0, v52
	v_max_f32_e32 v53, v53, v53
	v_max_f32_e32 v48, 0, v48
	v_max_f32_e32 v49, v49, v49
	v_max_f32_e32 v44, 0, v44
	v_max_f32_e32 v45, v45, v45
	v_max_f32_e32 v40, 0, v40
	v_max_f32_e32 v41, v41, v41
	v_max_f32_e32 v36, 0, v36
	v_max_f32_e32 v37, v37, v37
	v_max_f32_e32 v32, 0, v32
	v_max_f32_e32 v33, v33, v33
	v_max_f32_e32 v28, 0, v28
	v_max_f32_e32 v29, v29, v29
	v_max_f32_e32 v24, 0, v24
	v_max_f32_e32 v25, v25, v25
	v_max_f32_e32 v20, 0, v20
	v_max_f32_e32 v21, v21, v21
	v_max_f32_e32 v16, 0, v16
	v_max_f32_e32 v17, v17, v17
	v_max_f32_e32 v12, 0, v12
	v_max_f32_e32 v13, v13, v13
	v_max_f32_e32 v8, 0, v8
	v_max_f32_e32 v9, v9, v9
	v_max_f32_e32 v4, 0, v4
	v_max_f32_e32 v5, v5, v5
	v_max_f32_e32 v0, 0, v0
	v_max_f32_e32 v1, v1, v1
	v_lshl_or_b32 v65, v73, 1, v64
	v_mul_f32_e32 v60, v60, v60
	v_max_f32_e32 v61, 0, v61
	v_max_f32_e32 v62, v62, v62
	s_movk_i32 s4, 0x240
	v_mul_f32_e32 v56, v56, v56
	v_max_f32_e32 v57, 0, v57
	v_max_f32_e32 v58, v58, v58
	v_mul_f32_e32 v52, v52, v52
	v_max_f32_e32 v53, 0, v53
	v_max_f32_e32 v54, v54, v54
	v_mul_f32_e32 v48, v48, v48
	v_max_f32_e32 v49, 0, v49
	v_max_f32_e32 v50, v50, v50
	v_mul_f32_e32 v44, v44, v44
	v_max_f32_e32 v45, 0, v45
	v_max_f32_e32 v46, v46, v46
	v_mul_f32_e32 v40, v40, v40
	v_max_f32_e32 v41, 0, v41
	v_max_f32_e32 v42, v42, v42
	v_mul_f32_e32 v36, v36, v36
	v_max_f32_e32 v37, 0, v37
	v_max_f32_e32 v38, v38, v38
	v_mul_f32_e32 v32, v32, v32
	v_max_f32_e32 v33, 0, v33
	v_max_f32_e32 v34, v34, v34
	v_mul_f32_e32 v28, v28, v28
	v_max_f32_e32 v29, 0, v29
	v_max_f32_e32 v30, v30, v30
	v_mul_f32_e32 v24, v24, v24
	v_max_f32_e32 v25, 0, v25
	v_max_f32_e32 v26, v26, v26
	v_mul_f32_e32 v20, v20, v20
	v_max_f32_e32 v21, 0, v21
	v_max_f32_e32 v22, v22, v22
	v_mul_f32_e32 v16, v16, v16
	v_max_f32_e32 v17, 0, v17
	v_max_f32_e32 v18, v18, v18
	v_mul_f32_e32 v12, v12, v12
	v_max_f32_e32 v13, 0, v13
	v_max_f32_e32 v14, v14, v14
	v_mul_f32_e32 v8, v8, v8
	v_max_f32_e32 v9, 0, v9
	v_max_f32_e32 v10, v10, v10
	v_mul_f32_e32 v4, v4, v4
	v_max_f32_e32 v5, 0, v5
	v_max_f32_e32 v6, v6, v6
	v_mul_f32_e32 v0, v0, v0
	v_max_f32_e32 v1, 0, v1
	v_max_f32_e32 v2, v2, v2
	v_mul_f32_e32 v61, v61, v61
	v_max_f32_e32 v62, 0, v62
	v_max_f32_e32 v63, v63, v63
	v_cvt_pk_bf16_f32 v60, v60, s0
	v_mad_u32_u24 v65, v71, s4, v65
	v_mul_f32_e32 v57, v57, v57
	v_max_f32_e32 v58, 0, v58
	v_max_f32_e32 v59, v59, v59
	v_cvt_pk_bf16_f32 v56, v56, s0
	v_mul_f32_e32 v53, v53, v53
	v_max_f32_e32 v54, 0, v54
	v_max_f32_e32 v55, v55, v55
	v_cvt_pk_bf16_f32 v52, v52, s0
	v_mul_f32_e32 v49, v49, v49
	v_max_f32_e32 v50, 0, v50
	v_max_f32_e32 v51, v51, v51
	v_cvt_pk_bf16_f32 v48, v48, s0
	v_mul_f32_e32 v45, v45, v45
	v_max_f32_e32 v46, 0, v46
	v_max_f32_e32 v47, v47, v47
	v_cvt_pk_bf16_f32 v44, v44, s0
	v_mul_f32_e32 v41, v41, v41
	v_max_f32_e32 v42, 0, v42
	v_max_f32_e32 v43, v43, v43
	v_cvt_pk_bf16_f32 v40, v40, s0
	v_mul_f32_e32 v37, v37, v37
	v_max_f32_e32 v38, 0, v38
	v_max_f32_e32 v39, v39, v39
	v_cvt_pk_bf16_f32 v36, v36, s0
	v_mul_f32_e32 v33, v33, v33
	v_max_f32_e32 v34, 0, v34
	v_max_f32_e32 v35, v35, v35
	v_cvt_pk_bf16_f32 v32, v32, s0
	v_mul_f32_e32 v29, v29, v29
	v_max_f32_e32 v30, 0, v30
	v_max_f32_e32 v31, v31, v31
	v_cvt_pk_bf16_f32 v28, v28, s0
	v_mul_f32_e32 v25, v25, v25
	v_max_f32_e32 v26, 0, v26
	v_max_f32_e32 v27, v27, v27
	v_cvt_pk_bf16_f32 v24, v24, s0
	v_mul_f32_e32 v21, v21, v21
	v_max_f32_e32 v22, 0, v22
	v_max_f32_e32 v23, v23, v23
	v_cvt_pk_bf16_f32 v20, v20, s0
	v_mul_f32_e32 v17, v17, v17
	v_max_f32_e32 v18, 0, v18
	v_max_f32_e32 v19, v19, v19
	v_cvt_pk_bf16_f32 v16, v16, s0
	v_mul_f32_e32 v13, v13, v13
	v_max_f32_e32 v14, 0, v14
	v_max_f32_e32 v15, v15, v15
	v_cvt_pk_bf16_f32 v12, v12, s0
	v_mul_f32_e32 v9, v9, v9
	v_max_f32_e32 v10, 0, v10
	v_max_f32_e32 v11, v11, v11
	v_cvt_pk_bf16_f32 v8, v8, s0
	v_mul_f32_e32 v5, v5, v5
	v_max_f32_e32 v6, 0, v6
	v_max_f32_e32 v7, v7, v7
	v_cvt_pk_bf16_f32 v4, v4, s0
	v_mul_f32_e32 v1, v1, v1
	v_max_f32_e32 v2, 0, v2
	v_max_f32_e32 v3, v3, v3
	v_cvt_pk_bf16_f32 v0, v0, s0
	s_waitcnt vmcnt(0)
	s_barrier
	v_mul_f32_e32 v62, v62, v62
	v_max_f32_e32 v63, 0, v63
	ds_write_b16 v65, v60
	v_cvt_pk_bf16_f32 v60, v61, s0
	v_mul_f32_e32 v58, v58, v58
	v_max_f32_e32 v59, 0, v59
	ds_write_b16 v65, v56 offset:32
	v_cvt_pk_bf16_f32 v56, v57, s0
	v_mul_f32_e32 v54, v54, v54
	v_max_f32_e32 v55, 0, v55
	ds_write_b16 v65, v52 offset:64
	v_cvt_pk_bf16_f32 v52, v53, s0
	v_mul_f32_e32 v50, v50, v50
	v_max_f32_e32 v51, 0, v51
	ds_write_b16 v65, v48 offset:96
	v_cvt_pk_bf16_f32 v48, v49, s0
	v_mul_f32_e32 v46, v46, v46
	v_max_f32_e32 v47, 0, v47
	ds_write_b16 v65, v44 offset:2304
	v_cvt_pk_bf16_f32 v44, v45, s0
	v_mul_f32_e32 v42, v42, v42
	v_max_f32_e32 v43, 0, v43
	ds_write_b16 v65, v40 offset:2336
	v_cvt_pk_bf16_f32 v40, v41, s0
	v_mul_f32_e32 v38, v38, v38
	v_max_f32_e32 v39, 0, v39
	ds_write_b16 v65, v36 offset:2368
	v_cvt_pk_bf16_f32 v36, v37, s0
	v_mul_f32_e32 v34, v34, v34
	v_max_f32_e32 v35, 0, v35
	ds_write_b16 v65, v32 offset:2400
	v_cvt_pk_bf16_f32 v32, v33, s0
	v_mul_f32_e32 v30, v30, v30
	v_max_f32_e32 v31, 0, v31
	ds_write_b16 v65, v28 offset:4608
	v_cvt_pk_bf16_f32 v28, v29, s0
	v_mul_f32_e32 v26, v26, v26
	v_max_f32_e32 v27, 0, v27
	ds_write_b16 v65, v24 offset:4640
	v_cvt_pk_bf16_f32 v24, v25, s0
	v_mul_f32_e32 v22, v22, v22
	v_max_f32_e32 v23, 0, v23
	ds_write_b16 v65, v20 offset:4672
	v_cvt_pk_bf16_f32 v20, v21, s0
	v_mul_f32_e32 v18, v18, v18
	v_max_f32_e32 v19, 0, v19
	ds_write_b16 v65, v16 offset:4704
	v_cvt_pk_bf16_f32 v16, v17, s0
	v_mul_f32_e32 v14, v14, v14
	v_max_f32_e32 v15, 0, v15
	ds_write_b16 v65, v12 offset:6912
	v_cvt_pk_bf16_f32 v12, v13, s0
	v_mul_f32_e32 v10, v10, v10
	v_max_f32_e32 v11, 0, v11
	ds_write_b16 v65, v8 offset:6944
	v_cvt_pk_bf16_f32 v8, v9, s0
	v_mul_f32_e32 v6, v6, v6
	v_max_f32_e32 v7, 0, v7
	ds_write_b16 v65, v4 offset:6976
	v_cvt_pk_bf16_f32 v4, v5, s0
	v_mul_f32_e32 v2, v2, v2
	v_max_f32_e32 v3, 0, v3
	ds_write_b16 v65, v0 offset:7008
	v_cvt_pk_bf16_f32 v0, v1, s0
	v_mul_f32_e32 v63, v63, v63
	ds_write_b16 v65, v60 offset:144
	v_cvt_pk_bf16_f32 v60, v62, s0
	v_mul_f32_e32 v59, v59, v59
	ds_write_b16 v65, v56 offset:176
	v_cvt_pk_bf16_f32 v56, v58, s0
	v_mul_f32_e32 v55, v55, v55
	ds_write_b16 v65, v52 offset:208
	v_cvt_pk_bf16_f32 v52, v54, s0
	v_mul_f32_e32 v51, v51, v51
	ds_write_b16 v65, v48 offset:240
	v_cvt_pk_bf16_f32 v48, v50, s0
	v_mul_f32_e32 v47, v47, v47
	ds_write_b16 v65, v44 offset:2448
	v_cvt_pk_bf16_f32 v44, v46, s0
	v_mul_f32_e32 v43, v43, v43
	ds_write_b16 v65, v40 offset:2480
	v_cvt_pk_bf16_f32 v40, v42, s0
	v_mul_f32_e32 v39, v39, v39
	ds_write_b16 v65, v36 offset:2512
	v_cvt_pk_bf16_f32 v36, v38, s0
	v_mul_f32_e32 v35, v35, v35
	ds_write_b16 v65, v32 offset:2544
	v_cvt_pk_bf16_f32 v32, v34, s0
	v_mul_f32_e32 v31, v31, v31
	ds_write_b16 v65, v28 offset:4752
	v_cvt_pk_bf16_f32 v28, v30, s0
	v_mul_f32_e32 v27, v27, v27
	ds_write_b16 v65, v24 offset:4784
	v_cvt_pk_bf16_f32 v24, v26, s0
	v_mul_f32_e32 v23, v23, v23
	ds_write_b16 v65, v20 offset:4816
	v_cvt_pk_bf16_f32 v20, v22, s0
	v_mul_f32_e32 v19, v19, v19
	ds_write_b16 v65, v16 offset:4848
	v_cvt_pk_bf16_f32 v16, v18, s0
	v_mul_f32_e32 v15, v15, v15
	ds_write_b16 v65, v12 offset:7056
	v_cvt_pk_bf16_f32 v12, v14, s0
	v_mul_f32_e32 v11, v11, v11
	ds_write_b16 v65, v8 offset:7088
	v_cvt_pk_bf16_f32 v8, v10, s0
	v_mul_f32_e32 v7, v7, v7
	ds_write_b16 v65, v4 offset:7120
	v_cvt_pk_bf16_f32 v4, v6, s0
	v_mul_f32_e32 v3, v3, v3
	ds_write_b16 v65, v0 offset:7152
	v_cvt_pk_bf16_f32 v0, v2, s0
	v_add_u32_e32 v5, s1, v70
	s_ashr_i32 s1, s0, 31
	v_readlane_b32 s36, v246, 25
	ds_write_b16 v65, v60 offset:288
	v_cvt_pk_bf16_f32 v60, v63, s0
	ds_write_b16 v65, v56 offset:320
	v_cvt_pk_bf16_f32 v56, v59, s0
	ds_write_b16 v65, v52 offset:352
	v_cvt_pk_bf16_f32 v52, v55, s0
	ds_write_b16 v65, v48 offset:384
	v_cvt_pk_bf16_f32 v48, v51, s0
	ds_write_b16 v65, v44 offset:2592
	v_cvt_pk_bf16_f32 v44, v47, s0
	ds_write_b16 v65, v40 offset:2624
	v_cvt_pk_bf16_f32 v40, v43, s0
	ds_write_b16 v65, v36 offset:2656
	v_cvt_pk_bf16_f32 v36, v39, s0
	ds_write_b16 v65, v32 offset:2688
	v_cvt_pk_bf16_f32 v32, v35, s0
	ds_write_b16 v65, v28 offset:4896
	v_cvt_pk_bf16_f32 v28, v31, s0
	ds_write_b16 v65, v24 offset:4928
	v_cvt_pk_bf16_f32 v24, v27, s0
	ds_write_b16 v65, v20 offset:4960
	v_cvt_pk_bf16_f32 v20, v23, s0
	ds_write_b16 v65, v16 offset:4992
	v_cvt_pk_bf16_f32 v16, v19, s0
	ds_write_b16 v65, v12 offset:7200
	v_cvt_pk_bf16_f32 v12, v15, s0
	ds_write_b16 v65, v8 offset:7232
	v_cvt_pk_bf16_f32 v8, v11, s0
	ds_write_b16 v65, v4 offset:7264
	v_cvt_pk_bf16_f32 v4, v7, s0
	ds_write_b16 v65, v0 offset:7296
	v_cvt_pk_bf16_f32 v0, v3, s0
	s_lshl_b64 s[0:1], s[0:1], 1
	v_readlane_b32 s38, v246, 27
	ds_write_b16 v65, v0 offset:7440
	v_lshlrev_b32_e32 v0, 4, v69
	v_readlane_b32 s39, v246, 28
	s_add_u32 s0, s38, s0
	v_and_b32_e32 v0, 0x70, v0
	s_addc_u32 s1, s39, s1
	v_lshlrev_b32_e32 v136, 1, v134
	ds_write_b16 v65, v4 offset:7408
	v_or_b32_e32 v4, v64, v0
	v_lshl_add_u64 v[2:3], s[0:1], 0, v[136:137]
	s_movk_i32 s0, 0x90
	ds_write_b16 v65, v60 offset:432
	ds_write_b16 v65, v56 offset:464
	ds_write_b16 v65, v52 offset:496
	ds_write_b16 v65, v48 offset:528
	ds_write_b16 v65, v44 offset:2736
	ds_write_b16 v65, v40 offset:2768
	ds_write_b16 v65, v36 offset:2800
	ds_write_b16 v65, v32 offset:2832
	ds_write_b16 v65, v28 offset:5040
	ds_write_b16 v65, v24 offset:5072
	ds_write_b16 v65, v20 offset:5104
	ds_write_b16 v65, v16 offset:5136
	ds_write_b16 v65, v12 offset:7344
	ds_write_b16 v65, v8 offset:7376
	v_mov_b32_e32 v1, v137
	v_mad_u32_u24 v12, v68, s0, v4
	v_lshl_add_u64 v[8:9], v[2:3], 0, v[0:1]
	ds_read_b128 v[0:3], v12
	v_or_b32_e32 v13, v5, v68
	ds_read_b128 v[4:7], v12 offset:1152
	s_movk_i32 s4, 0x2080
	v_mad_i64_i32 v[10:11], s[0:1], v13, s4, v[8:9]
	s_waitcnt lgkmcnt(1)
	global_store_dwordx4 v[10:11], v[0:3], off
	s_add_i32 s6, s6, 1
	s_movk_i32 s36, 0x880
	v_or_b32_e32 v0, 8, v13
	v_mad_i64_i32 v[0:1], s[0:1], v0, s4, v[8:9]
	s_waitcnt lgkmcnt(0)
	global_store_dwordx4 v[0:1], v[4:7], off
	ds_read_b128 v[0:3], v12 offset:2304
	v_readlane_b32 s37, v246, 26
	v_or_b32_e32 v4, 16, v13
	v_mad_i64_i32 v[10:11], s[0:1], v4, s4, v[8:9]
	ds_read_b128 v[4:7], v12 offset:3456
	s_waitcnt lgkmcnt(1)
	global_store_dwordx4 v[10:11], v[0:3], off
	v_readlane_b32 s40, v246, 29
	v_readlane_b32 s41, v246, 30
	v_or_b32_e32 v0, 24, v13
	v_mad_i64_i32 v[0:1], s[0:1], v0, s4, v[8:9]
	s_waitcnt lgkmcnt(0)
	global_store_dwordx4 v[0:1], v[4:7], off
	ds_read_b128 v[0:3], v12 offset:4608
	v_readlane_b32 s42, v246, 31
	v_or_b32_e32 v4, 32, v13
	v_mad_i64_i32 v[10:11], s[0:1], v4, s4, v[8:9]
	ds_read_b128 v[4:7], v12 offset:5760
	s_waitcnt lgkmcnt(1)
	global_store_dwordx4 v[10:11], v[0:3], off
	v_readlane_b32 s43, v246, 32
	v_readlane_b32 s44, v246, 33
	v_or_b32_e32 v0, 40, v13
	v_mad_i64_i32 v[0:1], s[0:1], v0, s4, v[8:9]
	s_waitcnt lgkmcnt(0)
	global_store_dwordx4 v[0:1], v[4:7], off
	ds_read_b128 v[0:3], v12 offset:6912
	v_readlane_b32 s45, v246, 34
	v_or_b32_e32 v4, 48, v13
	v_mad_i64_i32 v[10:11], s[0:1], v4, s4, v[8:9]
	ds_read_b128 v[4:7], v12 offset:8064
	s_waitcnt lgkmcnt(1)
	global_store_dwordx4 v[10:11], v[0:3], off
	v_readlane_b32 s46, v246, 35
	v_readlane_b32 s47, v246, 36
	v_or_b32_e32 v0, 56, v13
	v_mad_i64_i32 v[0:1], s[0:1], v0, s4, v[8:9]
	s_mov_b64 s[4:5], 0
	v_readlane_b32 s48, v246, 37
	v_readlane_b32 s49, v246, 38
	v_readlane_b32 s50, v246, 39
	v_readlane_b32 s51, v246, 40
	s_waitcnt lgkmcnt(0)
	global_store_dwordx4 v[0:1], v[4:7], off
	s_barrier
	s_branch .LBB0_141

.LBB0_172:
	s_and_b32 s10, s9, 0x8000
	s_xor_b32 s11, s10, 0x8000
	v_add_u32_e32 v79, s11, v72
	v_lshl_add_u64 v[80:81], v[64:65], 0, s[6:7]
	v_readfirstlane_b32 s11, v79
	v_lshl_add_u64 v[82:83], v[80:81], 0, s[28:29]
	s_mov_b32 m0, s11
	v_lshl_add_u64 v[84:85], v[66:67], 0, s[6:7]
	global_load_lds_dwordx4 v[82:83], off
	v_add_u32_e32 v82, 0x4000, v79
	v_lshl_add_u64 v[86:87], v[84:85], 0, s[28:29]
	v_readfirstlane_b32 s11, v82
	s_mov_b32 m0, s11
	v_lshl_add_u64 v[82:83], v[80:81], 0, s[12:13]
	global_load_lds_dwordx4 v[86:87], off
	v_add_u32_e32 v86, 0x1000, v79
	s_nop 0
	v_readfirstlane_b32 s11, v86
	v_add_u32_e32 v86, 0x5000, v79
	s_mov_b32 m0, s11
	v_readfirstlane_b32 s11, v86
	v_add_u32_e32 v86, 0x2000, v79
	global_load_lds_dwordx4 v[82:83], off
	v_lshl_add_u64 v[82:83], v[84:85], 0, s[12:13]
	s_mov_b32 m0, s11
	v_readfirstlane_b32 s11, v86
	v_add_u32_e32 v86, 0x6000, v79
	global_load_lds_dwordx4 v[82:83], off
	v_lshl_add_u64 v[82:83], v[80:81], 0, s[16:17]
	s_mov_b32 m0, s11
	v_readfirstlane_b32 s11, v86
	global_load_lds_dwordx4 v[82:83], off
	v_lshl_add_u64 v[82:83], v[84:85], 0, s[16:17]
	s_mov_b32 m0, s11
	v_lshl_add_u64 v[80:81], v[80:81], 0, s[14:15]
	global_load_lds_dwordx4 v[82:83], off
	v_add_u32_e32 v82, 0x3000, v79
	v_add_u32_e32 v79, 0x7000, v79
	v_readfirstlane_b32 s11, v82
	s_mov_b32 m0, s11
	v_readfirstlane_b32 s11, v79
	global_load_lds_dwordx4 v[80:81], off
	v_lshl_add_u64 v[80:81], v[84:85], 0, s[14:15]
	s_mov_b32 m0, s11
	v_or_b32_e32 v79, s10, v78
	global_load_lds_dwordx4 v[80:81], off
	v_add_u32_e32 v100, v79, v73
	v_add_u32_e32 v79, v79, v74
	ds_read_b128 v[80:83], v100
	ds_read_b128 v[84:87], v100 offset:2048
	ds_read_b128 v[88:91], v79 offset:16384
	ds_read_b128 v[92:95], v79 offset:18432
	ds_read_b128 v[96:99], v100 offset:4096
	ds_read_b128 v[100:103], v100 offset:6144
	ds_read_b128 v[104:107], v79 offset:20480
	ds_read_b128 v[108:111], v79 offset:22528
	v_or_b32_e32 v79, s10, v77
	v_add_u32_e32 v132, v79, v73
	v_add_u32_e32 v79, v79, v74
	ds_read_b128 v[112:115], v132
	ds_read_b128 v[116:119], v132 offset:2048
	ds_read_b128 v[120:123], v79 offset:16384
	ds_read_b128 v[124:127], v79 offset:18432
	ds_read_b128 v[128:131], v132 offset:4096
	ds_read_b128 v[132:135], v132 offset:6144
	ds_read_b128 v[146:149], v79 offset:20480
	ds_read_b128 v[150:153], v79 offset:22528
	s_waitcnt lgkmcnt(0)
	v_mfma_f32_16x16x32_bf16 v[60:63], v[80:83], v[88:91], v[60:63]
	v_mfma_f32_16x16x32_bf16 v[56:59], v[80:83], v[92:95], v[56:59]
	v_mfma_f32_16x16x32_bf16 v[52:55], v[80:83], v[104:107], v[52:55]
	v_mfma_f32_16x16x32_bf16 v[48:51], v[80:83], v[108:111], v[48:51]
	v_mfma_f32_16x16x32_bf16 v[44:47], v[84:87], v[88:91], v[44:47]
	v_mfma_f32_16x16x32_bf16 v[40:43], v[84:87], v[92:95], v[40:43]
	v_mfma_f32_16x16x32_bf16 v[36:39], v[84:87], v[104:107], v[36:39]
	v_mfma_f32_16x16x32_bf16 v[32:35], v[84:87], v[108:111], v[32:35]
	v_mfma_f32_16x16x32_bf16 v[28:31], v[96:99], v[88:91], v[28:31]
	v_mfma_f32_16x16x32_bf16 v[24:27], v[96:99], v[92:95], v[24:27]
	v_mfma_f32_16x16x32_bf16 v[20:23], v[96:99], v[104:107], v[20:23]
	v_mfma_f32_16x16x32_bf16 v[16:19], v[96:99], v[108:111], v[16:19]
	v_mfma_f32_16x16x32_bf16 v[12:15], v[100:103], v[88:91], v[12:15]
	v_mfma_f32_16x16x32_bf16 v[8:11], v[100:103], v[92:95], v[8:11]
	v_mfma_f32_16x16x32_bf16 v[4:7], v[100:103], v[104:107], v[4:7]
	v_mfma_f32_16x16x32_bf16 v[0:3], v[100:103], v[108:111], v[0:3]
	v_mfma_f32_16x16x32_bf16 v[60:63], v[112:115], v[120:123], v[60:63]
	v_mfma_f32_16x16x32_bf16 v[56:59], v[112:115], v[124:127], v[56:59]
	v_mfma_f32_16x16x32_bf16 v[52:55], v[112:115], v[146:149], v[52:55]
	v_mfma_f32_16x16x32_bf16 v[48:51], v[112:115], v[150:153], v[48:51]
	v_mfma_f32_16x16x32_bf16 v[44:47], v[116:119], v[120:123], v[44:47]
	v_mfma_f32_16x16x32_bf16 v[40:43], v[116:119], v[124:127], v[40:43]
	v_mfma_f32_16x16x32_bf16 v[36:39], v[116:119], v[146:149], v[36:39]
	v_mfma_f32_16x16x32_bf16 v[32:35], v[116:119], v[150:153], v[32:35]
	v_mfma_f32_16x16x32_bf16 v[28:31], v[128:131], v[120:123], v[28:31]
	v_mfma_f32_16x16x32_bf16 v[24:27], v[128:131], v[124:127], v[24:27]
	v_mfma_f32_16x16x32_bf16 v[20:23], v[128:131], v[146:149], v[20:23]
	v_mfma_f32_16x16x32_bf16 v[16:19], v[128:131], v[150:153], v[16:19]
	v_mfma_f32_16x16x32_bf16 v[12:15], v[132:135], v[120:123], v[12:15]
	v_mfma_f32_16x16x32_bf16 v[8:11], v[132:135], v[124:127], v[8:11]
	v_mfma_f32_16x16x32_bf16 v[4:7], v[132:135], v[146:149], v[4:7]
	v_mfma_f32_16x16x32_bf16 v[0:3], v[132:135], v[150:153], v[0:3]
	s_waitcnt vmcnt(0)
	s_add_u32 s6, s6, 0x80
	s_addc_u32 s7, s7, 0
	s_add_i32 s9, s9, 0x8000
	s_cmpk_eq_i32 s6, 0x780
	s_barrier
	s_cbranch_scc0 .LBB0_172
	v_add_u32_e32 v72, v78, v73
	v_add_u32_e32 v102, v78, v74
	ds_read_b128 v[64:67], v72 offset:32768
	ds_read_b128 v[78:81], v72 offset:34816
	ds_read_b128 v[82:85], v102 offset:49152
	ds_read_b128 v[86:89], v102 offset:51200
	ds_read_b128 v[90:93], v72 offset:36864
	ds_read_b128 v[94:97], v72 offset:38912
	ds_read_b128 v[98:101], v102 offset:53248
	ds_read_b128 v[102:105], v102 offset:55296
	v_add_u32_e32 v72, v77, v73
	v_add_u32_e32 v73, v77, v74
	ds_read_b128 v[106:109], v72 offset:32768
	ds_read_b128 v[110:113], v72 offset:34816
	ds_read_b128 v[114:117], v73 offset:49152
	ds_read_b128 v[118:121], v73 offset:51200
	ds_read_b128 v[122:125], v72 offset:36864
	ds_read_b128 v[126:129], v72 offset:38912
	ds_read_b128 v[130:133], v73 offset:53248
	ds_read_b128 v[146:149], v73 offset:55296
	s_waitcnt lgkmcnt(13)
	v_mfma_f32_16x16x32_bf16 v[60:63], v[64:67], v[82:85], v[60:63]
	s_waitcnt lgkmcnt(12)
	v_mfma_f32_16x16x32_bf16 v[56:59], v[64:67], v[86:89], v[56:59]
	s_waitcnt lgkmcnt(9)
	v_mfma_f32_16x16x32_bf16 v[52:55], v[64:67], v[98:101], v[52:55]
	s_waitcnt lgkmcnt(8)
	v_mfma_f32_16x16x32_bf16 v[48:51], v[64:67], v[102:105], v[48:51]
	v_mfma_f32_16x16x32_bf16 v[44:47], v[78:81], v[82:85], v[44:47]
	v_mfma_f32_16x16x32_bf16 v[40:43], v[78:81], v[86:89], v[40:43]
	v_mfma_f32_16x16x32_bf16 v[36:39], v[78:81], v[98:101], v[36:39]
	v_mfma_f32_16x16x32_bf16 v[32:35], v[78:81], v[102:105], v[32:35]
	v_mfma_f32_16x16x32_bf16 v[28:31], v[90:93], v[82:85], v[28:31]
	v_mfma_f32_16x16x32_bf16 v[24:27], v[90:93], v[86:89], v[24:27]
	v_mfma_f32_16x16x32_bf16 v[20:23], v[90:93], v[98:101], v[20:23]
	v_mfma_f32_16x16x32_bf16 v[16:19], v[90:93], v[102:105], v[16:19]
	v_mfma_f32_16x16x32_bf16 v[12:15], v[94:97], v[82:85], v[12:15]
	v_mfma_f32_16x16x32_bf16 v[8:11], v[94:97], v[86:89], v[8:11]
	v_mfma_f32_16x16x32_bf16 v[4:7], v[94:97], v[98:101], v[4:7]
	v_mfma_f32_16x16x32_bf16 v[0:3], v[94:97], v[102:105], v[0:3]
	s_waitcnt lgkmcnt(5)
	v_mfma_f32_16x16x32_bf16 v[78:81], v[106:109], v[114:117], v[60:63]
	s_waitcnt lgkmcnt(4)
	v_mfma_f32_16x16x32_bf16 v[56:59], v[106:109], v[118:121], v[56:59]
	s_waitcnt lgkmcnt(1)
	v_mfma_f32_16x16x32_bf16 v[52:55], v[106:109], v[130:133], v[52:55]
	s_waitcnt lgkmcnt(0)
	v_mfma_f32_16x16x32_bf16 v[48:51], v[106:109], v[146:149], v[48:51]
	v_mfma_f32_16x16x32_bf16 v[44:47], v[110:113], v[114:117], v[44:47]
	v_mfma_f32_16x16x32_bf16 v[40:43], v[110:113], v[118:121], v[40:43]
	v_mfma_f32_16x16x32_bf16 v[36:39], v[110:113], v[130:133], v[36:39]
	v_mfma_f32_16x16x32_bf16 v[32:35], v[110:113], v[146:149], v[32:35]
	v_mfma_f32_16x16x32_bf16 v[28:31], v[122:125], v[114:117], v[28:31]
	v_mfma_f32_16x16x32_bf16 v[24:27], v[122:125], v[118:121], v[24:27]
	v_mfma_f32_16x16x32_bf16 v[20:23], v[122:125], v[130:133], v[20:23]
	v_mfma_f32_16x16x32_bf16 v[16:19], v[122:125], v[146:149], v[16:19]
	v_mfma_f32_16x16x32_bf16 v[12:15], v[126:129], v[114:117], v[12:15]
	v_mfma_f32_16x16x32_bf16 v[8:11], v[126:129], v[118:121], v[8:11]
	v_mfma_f32_16x16x32_bf16 v[4:7], v[126:129], v[130:133], v[4:7]
	v_mfma_f32_16x16x32_bf16 v[0:3], v[126:129], v[146:149], v[0:3]
	v_add_u32_e32 v72, s5, v69
	v_add_u32_e32 v61, 0xfffff000, v72
	s_movk_i32 s6, 0x2400
	v_lshl_or_b32 v60, v75, 2, v72
	v_lshrrev_b32_e32 v61, 12, v61
	s_movk_i32 s9, 0xfff
	v_mul_lo_u32 v74, v68, s6
	v_add_u32_e32 v61, 1, v61
	v_cmp_lt_i32_e32 vcc, s9, v60
	v_readlane_b32 s6, v245, 44
	v_readlane_b32 s7, v245, 45
	v_cndmask_b32_e32 v136, 0, v61, vcc
	v_lshl_add_u64 v[66:67], v[136:137], 0, s[0:1]
	v_mov_b64_e32 v[64:65], s[6:7]
	s_movk_i32 s5, 0x6000
	v_mad_u64_u32 v[68:69], s[6:7], v66, s5, v[64:65]
	v_or_b32_e32 v66, 1, v60
	v_mad_i32_i24 v69, v67, s5, v69
	v_ashrrev_i32_e32 v67, 31, v66
	v_lshlrev_b64 v[84:85], 12, v[66:67]
	v_or_b32_e32 v66, 2, v60
	v_and_b32_e32 v73, 64, v71
	v_ashrrev_i32_e32 v67, 31, v66
	v_or3_b32 v62, v76, s4, v73
	v_lshlrev_b64 v[86:87], 12, v[66:67]
	v_or_b32_e32 v66, 3, v60
	v_readlane_b32 s36, v247, 57
	v_ashrrev_i32_e32 v61, 31, v60
	v_ashrrev_i32_e32 v67, 31, v66
	v_ashrrev_i32_e32 v63, 31, v62
	v_readlane_b32 s46, v246, 3
	v_readlane_b32 s47, v246, 4
	v_lshlrev_b64 v[82:83], 12, v[60:61]
	v_lshlrev_b64 v[88:89], 12, v[66:67]
	v_lshlrev_b64 v[66:67], 2, v[62:63]
	v_lshl_add_u64 v[62:63], v[62:63], 1, s[46:47]
	v_lshl_add_u64 v[82:83], v[62:63], 0, v[82:83]
	s_waitcnt vmcnt(0)
	s_barrier
	global_load_ushort v77, v[82:83], off
	v_lshl_add_u64 v[68:69], v[68:69], 0, v[66:67]
	global_load_dword v61, v[68:69], off
	v_lshl_add_u64 v[84:85], v[62:63], 0, v[84:85]
	s_movk_i32 s6, 0x240
	s_movk_i32 s36, 0x880
	v_readlane_b32 s37, v247, 58
	v_readlane_b32 s38, v247, 59
	v_readlane_b32 s39, v247, 60
	v_readlane_b32 s40, v247, 61
	v_readlane_b32 s41, v247, 62
	v_readlane_b32 s42, v247, 63
	v_readlane_b32 s43, v246, 0
	v_readlane_b32 s44, v246, 1
	v_readlane_b32 s45, v246, 2
	v_readlane_b32 s48, v246, 5
	v_readlane_b32 s49, v246, 6
	v_readlane_b32 s50, v246, 7
	v_readlane_b32 s51, v246, 8
	s_waitcnt vmcnt(1)
	v_lshlrev_b32_e32 v77, 16, v77
	v_mul_f32_e32 v77, 0x3fd744fd, v77
	s_waitcnt vmcnt(0)
	v_fmac_f32_e32 v77, v78, v61
	global_load_ushort v78, v[84:85], off
	s_waitcnt vmcnt(0)
	v_lshlrev_b32_e32 v78, 16, v78
	v_mul_f32_e32 v90, 0x3fd744fd, v78
	v_fmac_f32_e32 v90, v79, v61
	v_lshl_add_u64 v[78:79], v[62:63], 0, v[86:87]
	global_load_ushort v86, v[78:79], off
	s_waitcnt vmcnt(0)
	v_lshlrev_b32_e32 v86, 16, v86
	v_mul_f32_e32 v91, 0x3fd744fd, v86
	v_lshl_add_u64 v[86:87], v[62:63], 0, v[88:89]
	v_fmac_f32_e32 v91, v80, v61
	global_load_ushort v80, v[86:87], off
	s_waitcnt vmcnt(0)
	v_lshlrev_b32_e32 v80, 16, v80
	v_mul_f32_e32 v80, 0x3fd744fd, v80
	v_fmac_f32_e32 v80, v81, v61
	v_lshl_or_b32 v61, v76, 1, v74
	v_mad_u32_u24 v61, v75, s6, v61
	v_cvt_pk_bf16_f32 v75, v90, s0
	ds_write_b16 v61, v75 offset:144
	v_cvt_pk_bf16_f32 v75, v91, s0
	v_cvt_pk_bf16_f32 v76, v77, s0
	ds_write_b16 v61, v75 offset:288
	v_cvt_pk_bf16_f32 v75, v80, s0
	ds_write_b16 v61, v76
	ds_write_b16 v61, v75 offset:432
	global_load_dword v75, v[68:69], off offset:64
	global_load_ushort v76, v[82:83], off offset:32
	s_waitcnt vmcnt(0)
	v_lshlrev_b32_e32 v76, 16, v76
	v_mul_f32_e32 v76, 0x3fd744fd, v76
	v_fmac_f32_e32 v76, v56, v75
	global_load_ushort v56, v[84:85], off offset:32
	s_waitcnt vmcnt(0)
	v_lshlrev_b32_e32 v56, 16, v56
	v_mul_f32_e32 v56, 0x3fd744fd, v56
	v_fmac_f32_e32 v56, v57, v75
	global_load_ushort v57, v[78:79], off offset:32
	v_cvt_pk_bf16_f32 v56, v56, s0
	ds_write_b16 v61, v56 offset:176
	s_waitcnt vmcnt(0)
	v_lshlrev_b32_e32 v57, 16, v57
	v_mul_f32_e32 v57, 0x3fd744fd, v57
	v_fmac_f32_e32 v57, v58, v75
	global_load_ushort v58, v[86:87], off offset:32
	v_cvt_pk_bf16_f32 v56, v57, s0
	ds_write_b16 v61, v56 offset:320
	s_waitcnt vmcnt(0)
	v_lshlrev_b32_e32 v58, 16, v58
	v_mul_f32_e32 v58, 0x3fd744fd, v58
	v_fmac_f32_e32 v58, v59, v75
	v_cvt_pk_bf16_f32 v59, v76, s0
	v_cvt_pk_bf16_f32 v56, v58, s0
	ds_write_b16 v61, v59 offset:32
	ds_write_b16 v61, v56 offset:464
	global_load_dword v56, v[68:69], off offset:128
	global_load_ushort v57, v[82:83], off offset:64
	s_waitcnt vmcnt(0)
	v_lshlrev_b32_e32 v57, 16, v57
	v_mul_f32_e32 v57, 0x3fd744fd, v57
	v_fmac_f32_e32 v57, v52, v56
	global_load_ushort v52, v[84:85], off offset:64
	s_waitcnt vmcnt(0)
	v_lshlrev_b32_e32 v52, 16, v52
	v_mul_f32_e32 v52, 0x3fd744fd, v52
	v_fmac_f32_e32 v52, v53, v56
	global_load_ushort v53, v[78:79], off offset:64
	v_cvt_pk_bf16_f32 v52, v52, s0
	ds_write_b16 v61, v52 offset:208
	s_waitcnt vmcnt(0)
	v_lshlrev_b32_e32 v53, 16, v53
	v_mul_f32_e32 v53, 0x3fd744fd, v53
	v_fmac_f32_e32 v53, v54, v56
	global_load_ushort v54, v[86:87], off offset:64
	v_cvt_pk_bf16_f32 v52, v53, s0
	ds_write_b16 v61, v52 offset:352
	s_waitcnt vmcnt(0)
	v_lshlrev_b32_e32 v54, 16, v54
	v_mul_f32_e32 v54, 0x3fd744fd, v54
	v_fmac_f32_e32 v54, v55, v56
	v_cvt_pk_bf16_f32 v55, v57, s0
	v_cvt_pk_bf16_f32 v52, v54, s0
	ds_write_b16 v61, v55 offset:64
	ds_write_b16 v61, v52 offset:496
	global_load_dword v52, v[68:69], off offset:192
	global_load_ushort v53, v[82:83], off offset:96
	v_or_b32_e32 v54, 18, v60
	v_ashrrev_i32_e32 v55, 31, v54
	v_lshlrev_b64 v[56:57], 12, v[54:55]
	v_or_b32_e32 v54, 19, v60
	v_ashrrev_i32_e32 v55, 31, v54
	v_lshlrev_b64 v[58:59], 12, v[54:55]
	s_waitcnt vmcnt(0)
	v_lshlrev_b32_e32 v53, 16, v53
	v_mul_f32_e32 v53, 0x3fd744fd, v53
	v_fmac_f32_e32 v53, v48, v52
	global_load_ushort v48, v[84:85], off offset:96
	s_waitcnt vmcnt(0)
	v_lshlrev_b32_e32 v48, 16, v48
	v_mul_f32_e32 v48, 0x3fd744fd, v48
	v_fmac_f32_e32 v48, v49, v52
	global_load_ushort v49, v[78:79], off offset:96
	v_cvt_pk_bf16_f32 v48, v48, s0
	ds_write_b16 v61, v48 offset:240
	s_waitcnt vmcnt(0)
	v_lshlrev_b32_e32 v49, 16, v49
	v_mul_f32_e32 v49, 0x3fd744fd, v49
	v_fmac_f32_e32 v49, v50, v52
	global_load_ushort v50, v[86:87], off offset:96
	v_cvt_pk_bf16_f32 v48, v49, s0
	ds_write_b16 v61, v48 offset:384
	v_add_u32_e32 v49, 0xfffff010, v72
	v_lshrrev_b32_e32 v49, 12, v49
	v_add_u32_e32 v49, 1, v49
	s_waitcnt vmcnt(0)
	v_lshlrev_b32_e32 v50, 16, v50
	v_mul_f32_e32 v50, 0x3fd744fd, v50
	v_fmac_f32_e32 v50, v51, v52
	v_cvt_pk_bf16_f32 v48, v50, s0
	ds_write_b16 v61, v48 offset:528
	v_or_b32_e32 v48, 16, v60
	v_cmp_lt_i32_e32 vcc, s9, v48
	v_cvt_pk_bf16_f32 v51, v53, s0
	ds_write_b16 v61, v51 offset:96
	v_cndmask_b32_e32 v136, 0, v49, vcc
	v_ashrrev_i32_e32 v49, 31, v48
	v_lshl_add_u64 v[50:51], v[136:137], 0, s[0:1]
	v_lshlrev_b64 v[48:49], 12, v[48:49]
	v_mad_u64_u32 v[52:53], s[6:7], v50, s5, v[64:65]
	v_lshl_add_u64 v[54:55], v[62:63], 0, v[48:49]
	v_mad_i32_i24 v53, v51, s5, v53
	global_load_ushort v48, v[54:55], off
	v_lshl_add_u64 v[52:53], v[52:53], 0, v[66:67]
	global_load_dword v68, v[52:53], off
	v_or_b32_e32 v50, 17, v60
	v_ashrrev_i32_e32 v51, 31, v50
	v_lshlrev_b64 v[50:51], 12, v[50:51]
	s_waitcnt vmcnt(1)
	v_lshlrev_b32_e32 v48, 16, v48
	v_mul_f32_e32 v69, 0x3fd744fd, v48
	v_lshl_add_u64 v[48:49], v[62:63], 0, v[50:51]
	s_waitcnt vmcnt(0)
	v_fmac_f32_e32 v69, v44, v68
	global_load_ushort v44, v[48:49], off
	v_lshl_add_u64 v[50:51], v[62:63], 0, v[56:57]
	s_waitcnt vmcnt(0)
	v_lshlrev_b32_e32 v44, 16, v44
	v_mul_f32_e32 v75, 0x3fd744fd, v44
	global_load_ushort v44, v[50:51], off
	v_fmac_f32_e32 v75, v45, v68
	s_waitcnt vmcnt(0)
	v_lshlrev_b32_e32 v44, 16, v44
	v_mul_f32_e32 v56, 0x3fd744fd, v44
	v_lshl_add_u64 v[44:45], v[62:63], 0, v[58:59]
	v_fmac_f32_e32 v56, v46, v68
	global_load_ushort v46, v[44:45], off
	s_waitcnt vmcnt(0)
	v_lshlrev_b32_e32 v46, 16, v46
	v_mul_f32_e32 v46, 0x3fd744fd, v46
	v_fmac_f32_e32 v46, v47, v68
	v_cvt_pk_bf16_f32 v47, v69, s0
	ds_write_b16 v61, v47 offset:2304
	v_cvt_pk_bf16_f32 v47, v75, s0
	ds_write_b16 v61, v47 offset:2448
	v_cvt_pk_bf16_f32 v47, v56, s0
	v_cvt_pk_bf16_f32 v46, v46, s0
	ds_write_b16 v61, v47 offset:2592
	ds_write_b16 v61, v46 offset:2736
	global_load_dword v46, v[52:53], off offset:64
	global_load_ushort v47, v[54:55], off offset:32
	s_waitcnt vmcnt(0)
	v_lshlrev_b32_e32 v47, 16, v47
	v_mul_f32_e32 v47, 0x3fd744fd, v47
	v_fmac_f32_e32 v47, v40, v46
	global_load_ushort v40, v[48:49], off offset:32
	s_waitcnt vmcnt(0)
	v_lshlrev_b32_e32 v40, 16, v40
	v_mul_f32_e32 v40, 0x3fd744fd, v40
	v_fmac_f32_e32 v40, v41, v46
	global_load_ushort v41, v[50:51], off offset:32
	v_cvt_pk_bf16_f32 v40, v40, s0
	ds_write_b16 v61, v40 offset:2480
	s_waitcnt vmcnt(0)
	v_lshlrev_b32_e32 v41, 16, v41
	v_mul_f32_e32 v41, 0x3fd744fd, v41
	v_fmac_f32_e32 v41, v42, v46
	global_load_ushort v42, v[44:45], off offset:32
	v_cvt_pk_bf16_f32 v40, v41, s0
	ds_write_b16 v61, v40 offset:2624
	s_waitcnt vmcnt(0)
	v_lshlrev_b32_e32 v42, 16, v42
	v_mul_f32_e32 v42, 0x3fd744fd, v42
	v_fmac_f32_e32 v42, v43, v46
	v_cvt_pk_bf16_f32 v43, v47, s0
	v_cvt_pk_bf16_f32 v40, v42, s0
	ds_write_b16 v61, v43 offset:2336
	ds_write_b16 v61, v40 offset:2768
	global_load_dword v40, v[52:53], off offset:128
	global_load_ushort v41, v[54:55], off offset:64
	s_waitcnt vmcnt(0)
	v_lshlrev_b32_e32 v41, 16, v41
	v_mul_f32_e32 v41, 0x3fd744fd, v41
	v_fmac_f32_e32 v41, v36, v40
	global_load_ushort v36, v[48:49], off offset:64
	s_waitcnt vmcnt(0)
	v_lshlrev_b32_e32 v36, 16, v36
	v_mul_f32_e32 v36, 0x3fd744fd, v36
	v_fmac_f32_e32 v36, v37, v40
	global_load_ushort v37, v[50:51], off offset:64
	v_cvt_pk_bf16_f32 v36, v36, s0
	ds_write_b16 v61, v36 offset:2512
	s_waitcnt vmcnt(0)
	v_lshlrev_b32_e32 v37, 16, v37
	v_mul_f32_e32 v37, 0x3fd744fd, v37
	v_fmac_f32_e32 v37, v38, v40
	global_load_ushort v38, v[44:45], off offset:64
	v_cvt_pk_bf16_f32 v36, v37, s0
	ds_write_b16 v61, v36 offset:2656
	s_waitcnt vmcnt(0)
	v_lshlrev_b32_e32 v38, 16, v38
	v_mul_f32_e32 v38, 0x3fd744fd, v38
	v_fmac_f32_e32 v38, v39, v40
	v_cvt_pk_bf16_f32 v39, v41, s0
	v_cvt_pk_bf16_f32 v36, v38, s0
	ds_write_b16 v61, v39 offset:2368
	ds_write_b16 v61, v36 offset:2800
	global_load_dword v36, v[52:53], off offset:192
	global_load_ushort v37, v[54:55], off offset:96
	v_or_b32_e32 v38, 34, v60
	v_ashrrev_i32_e32 v39, 31, v38
	v_lshlrev_b64 v[40:41], 12, v[38:39]
	v_or_b32_e32 v38, 35, v60
	v_ashrrev_i32_e32 v39, 31, v38
	v_lshlrev_b64 v[42:43], 12, v[38:39]
	s_waitcnt vmcnt(0)
	v_lshlrev_b32_e32 v37, 16, v37
	v_mul_f32_e32 v37, 0x3fd744fd, v37
	v_fmac_f32_e32 v37, v32, v36
	global_load_ushort v32, v[48:49], off offset:96
	s_waitcnt vmcnt(0)
	v_lshlrev_b32_e32 v32, 16, v32
	v_mul_f32_e32 v32, 0x3fd744fd, v32
	v_fmac_f32_e32 v32, v33, v36
	global_load_ushort v33, v[50:51], off offset:96
	v_cvt_pk_bf16_f32 v32, v32, s0
	ds_write_b16 v61, v32 offset:2544
	s_waitcnt vmcnt(0)
	v_lshlrev_b32_e32 v33, 16, v33
	v_mul_f32_e32 v33, 0x3fd744fd, v33
	v_fmac_f32_e32 v33, v34, v36
	global_load_ushort v34, v[44:45], off offset:96
	v_cvt_pk_bf16_f32 v32, v33, s0
	ds_write_b16 v61, v32 offset:2688
	v_add_u32_e32 v33, 0xfffff020, v72
	v_lshrrev_b32_e32 v33, 12, v33
	v_add_u32_e32 v33, 1, v33
	s_waitcnt vmcnt(0)
	v_lshlrev_b32_e32 v34, 16, v34
	v_mul_f32_e32 v34, 0x3fd744fd, v34
	v_fmac_f32_e32 v34, v35, v36
	v_cvt_pk_bf16_f32 v32, v34, s0
	ds_write_b16 v61, v32 offset:2832
	v_or_b32_e32 v32, 32, v60
	v_cmp_lt_i32_e32 vcc, s9, v32
	v_cvt_pk_bf16_f32 v35, v37, s0
	ds_write_b16 v61, v35 offset:2400
	v_cndmask_b32_e32 v136, 0, v33, vcc
	v_ashrrev_i32_e32 v33, 31, v32
	v_lshl_add_u64 v[34:35], v[136:137], 0, s[0:1]
	v_lshlrev_b64 v[32:33], 12, v[32:33]
	v_mad_u64_u32 v[36:37], s[6:7], v34, s5, v[64:65]
	v_lshl_add_u64 v[38:39], v[62:63], 0, v[32:33]
	v_mad_i32_i24 v37, v35, s5, v37
	global_load_ushort v32, v[38:39], off
	v_lshl_add_u64 v[36:37], v[36:37], 0, v[66:67]
	global_load_dword v44, v[36:37], off
	v_or_b32_e32 v34, 33, v60
	v_ashrrev_i32_e32 v35, 31, v34
	v_lshlrev_b64 v[34:35], 12, v[34:35]
	s_waitcnt vmcnt(1)
	v_lshlrev_b32_e32 v32, 16, v32
	v_mul_f32_e32 v45, 0x3fd744fd, v32
	v_lshl_add_u64 v[32:33], v[62:63], 0, v[34:35]
	s_waitcnt vmcnt(0)
	v_fmac_f32_e32 v45, v28, v44
	global_load_ushort v28, v[32:33], off
	v_lshl_add_u64 v[34:35], v[62:63], 0, v[40:41]
	s_waitcnt vmcnt(0)
	v_lshlrev_b32_e32 v28, 16, v28
	v_mul_f32_e32 v46, 0x3fd744fd, v28
	global_load_ushort v28, v[34:35], off
	v_fmac_f32_e32 v46, v29, v44
	s_waitcnt vmcnt(0)
	v_lshlrev_b32_e32 v28, 16, v28
	v_mul_f32_e32 v40, 0x3fd744fd, v28
	v_lshl_add_u64 v[28:29], v[62:63], 0, v[42:43]
	v_fmac_f32_e32 v40, v30, v44
	global_load_ushort v30, v[28:29], off
	s_waitcnt vmcnt(0)
	v_lshlrev_b32_e32 v30, 16, v30
	v_mul_f32_e32 v30, 0x3fd744fd, v30
	v_fmac_f32_e32 v30, v31, v44
	v_cvt_pk_bf16_f32 v31, v45, s0
	ds_write_b16 v61, v31 offset:4608
	v_cvt_pk_bf16_f32 v31, v46, s0
	ds_write_b16 v61, v31 offset:4752
	v_cvt_pk_bf16_f32 v31, v40, s0
	v_cvt_pk_bf16_f32 v30, v30, s0
	ds_write_b16 v61, v31 offset:4896
	ds_write_b16 v61, v30 offset:5040
	global_load_dword v30, v[36:37], off offset:64
	global_load_ushort v31, v[38:39], off offset:32
	s_waitcnt vmcnt(0)
	v_lshlrev_b32_e32 v31, 16, v31
	v_mul_f32_e32 v31, 0x3fd744fd, v31
	v_fmac_f32_e32 v31, v24, v30
	global_load_ushort v24, v[32:33], off offset:32
	s_waitcnt vmcnt(0)
	v_lshlrev_b32_e32 v24, 16, v24
	v_mul_f32_e32 v24, 0x3fd744fd, v24
	v_fmac_f32_e32 v24, v25, v30
	global_load_ushort v25, v[34:35], off offset:32
	v_cvt_pk_bf16_f32 v24, v24, s0
	ds_write_b16 v61, v24 offset:4784
	s_waitcnt vmcnt(0)
	v_lshlrev_b32_e32 v25, 16, v25
	v_mul_f32_e32 v25, 0x3fd744fd, v25
	v_fmac_f32_e32 v25, v26, v30
	global_load_ushort v26, v[28:29], off offset:32
	v_cvt_pk_bf16_f32 v24, v25, s0
	ds_write_b16 v61, v24 offset:4928
	s_waitcnt vmcnt(0)
	v_lshlrev_b32_e32 v26, 16, v26
	v_mul_f32_e32 v26, 0x3fd744fd, v26
	v_fmac_f32_e32 v26, v27, v30
	v_cvt_pk_bf16_f32 v27, v31, s0
	v_cvt_pk_bf16_f32 v24, v26, s0
	ds_write_b16 v61, v27 offset:4640
	ds_write_b16 v61, v24 offset:5072
	global_load_dword v24, v[36:37], off offset:128
	global_load_ushort v25, v[38:39], off offset:64
	s_waitcnt vmcnt(0)
	v_lshlrev_b32_e32 v25, 16, v25
	v_mul_f32_e32 v25, 0x3fd744fd, v25
	v_fmac_f32_e32 v25, v20, v24
	global_load_ushort v20, v[32:33], off offset:64
	s_waitcnt vmcnt(0)
	v_lshlrev_b32_e32 v20, 16, v20
	v_mul_f32_e32 v20, 0x3fd744fd, v20
	v_fmac_f32_e32 v20, v21, v24
	global_load_ushort v21, v[34:35], off offset:64
	v_cvt_pk_bf16_f32 v20, v20, s0
	ds_write_b16 v61, v20 offset:4816
	s_waitcnt vmcnt(0)
	v_lshlrev_b32_e32 v21, 16, v21
	v_mul_f32_e32 v21, 0x3fd744fd, v21
	v_fmac_f32_e32 v21, v22, v24
	global_load_ushort v22, v[28:29], off offset:64
	v_cvt_pk_bf16_f32 v20, v21, s0
	ds_write_b16 v61, v20 offset:4960
	s_waitcnt vmcnt(0)
	v_lshlrev_b32_e32 v22, 16, v22
	v_mul_f32_e32 v22, 0x3fd744fd, v22
	v_fmac_f32_e32 v22, v23, v24
	v_cvt_pk_bf16_f32 v23, v25, s0
	v_cvt_pk_bf16_f32 v20, v22, s0
	ds_write_b16 v61, v23 offset:4672
	ds_write_b16 v61, v20 offset:5104
	global_load_dword v20, v[36:37], off offset:192
	global_load_ushort v21, v[38:39], off offset:96
	v_or_b32_e32 v22, 50, v60
	v_ashrrev_i32_e32 v23, 31, v22
	v_lshlrev_b64 v[24:25], 12, v[22:23]
	v_or_b32_e32 v22, 51, v60
	v_ashrrev_i32_e32 v23, 31, v22
	v_lshlrev_b64 v[26:27], 12, v[22:23]
	s_waitcnt vmcnt(0)
	v_lshlrev_b32_e32 v21, 16, v21
	v_mul_f32_e32 v21, 0x3fd744fd, v21
	v_fmac_f32_e32 v21, v16, v20
	global_load_ushort v16, v[32:33], off offset:96
	s_waitcnt vmcnt(0)
	v_lshlrev_b32_e32 v16, 16, v16
	v_mul_f32_e32 v16, 0x3fd744fd, v16
	v_fmac_f32_e32 v16, v17, v20
	global_load_ushort v17, v[34:35], off offset:96
	v_cvt_pk_bf16_f32 v16, v16, s0
	ds_write_b16 v61, v16 offset:4848
	s_waitcnt vmcnt(0)
	v_lshlrev_b32_e32 v17, 16, v17
	v_mul_f32_e32 v17, 0x3fd744fd, v17
	v_fmac_f32_e32 v17, v18, v20
	global_load_ushort v18, v[28:29], off offset:96
	v_cvt_pk_bf16_f32 v16, v17, s0
	ds_write_b16 v61, v16 offset:4992
	v_add_u32_e32 v17, 0xfffff030, v72
	v_lshrrev_b32_e32 v17, 12, v17
	v_add_u32_e32 v17, 1, v17
	s_waitcnt vmcnt(0)
	v_lshlrev_b32_e32 v18, 16, v18
	v_mul_f32_e32 v18, 0x3fd744fd, v18
	v_fmac_f32_e32 v18, v19, v20
	v_cvt_pk_bf16_f32 v16, v18, s0
	ds_write_b16 v61, v16 offset:5136
	v_or_b32_e32 v16, 48, v60
	v_cmp_lt_i32_e32 vcc, s9, v16
	v_cvt_pk_bf16_f32 v19, v21, s0
	ds_write_b16 v61, v19 offset:4704
	v_cndmask_b32_e32 v136, 0, v17, vcc
	v_ashrrev_i32_e32 v17, 31, v16
	v_lshl_add_u64 v[18:19], v[136:137], 0, s[0:1]
	v_lshlrev_b64 v[16:17], 12, v[16:17]
	v_mad_u64_u32 v[20:21], s[6:7], v18, s5, v[64:65]
	v_lshl_add_u64 v[22:23], v[62:63], 0, v[16:17]
	v_mad_i32_i24 v21, v19, s5, v21
	global_load_ushort v16, v[22:23], off
	v_lshl_add_u64 v[20:21], v[20:21], 0, v[66:67]
	global_load_dword v28, v[20:21], off
	v_or_b32_e32 v18, 49, v60
	v_ashrrev_i32_e32 v19, 31, v18
	v_lshlrev_b64 v[18:19], 12, v[18:19]
	s_ashr_i32 s5, s4, 31
	s_lshl_b64 s[4:5], s[4:5], 1
	s_add_u32 s4, s46, s4
	s_addc_u32 s5, s47, s5
	v_lshlrev_b32_e32 v136, 1, v73
	s_add_i32 s8, s8, 1
	s_mov_b64 s[6:7], 0
	s_waitcnt vmcnt(1)
	v_lshlrev_b32_e32 v16, 16, v16
	v_mul_f32_e32 v29, 0x3fd744fd, v16
	v_lshl_add_u64 v[16:17], v[62:63], 0, v[18:19]
	s_waitcnt vmcnt(0)
	v_fmac_f32_e32 v29, v12, v28
	global_load_ushort v12, v[16:17], off
	v_lshl_add_u64 v[18:19], v[62:63], 0, v[24:25]
	s_waitcnt vmcnt(0)
	v_lshlrev_b32_e32 v12, 16, v12
	v_mul_f32_e32 v30, 0x3fd744fd, v12
	global_load_ushort v12, v[18:19], off
	v_fmac_f32_e32 v30, v13, v28
	s_waitcnt vmcnt(0)
	v_lshlrev_b32_e32 v12, 16, v12
	v_mul_f32_e32 v24, 0x3fd744fd, v12
	v_lshl_add_u64 v[12:13], v[62:63], 0, v[26:27]
	v_fmac_f32_e32 v24, v14, v28
	global_load_ushort v14, v[12:13], off
	s_waitcnt vmcnt(0)
	v_lshlrev_b32_e32 v14, 16, v14
	v_mul_f32_e32 v14, 0x3fd744fd, v14
	v_fmac_f32_e32 v14, v15, v28
	v_cvt_pk_bf16_f32 v15, v29, s0
	ds_write_b16 v61, v15 offset:6912
	v_cvt_pk_bf16_f32 v15, v30, s0
	ds_write_b16 v61, v15 offset:7056
	v_cvt_pk_bf16_f32 v15, v24, s0
	v_cvt_pk_bf16_f32 v14, v14, s0
	ds_write_b16 v61, v15 offset:7200
	ds_write_b16 v61, v14 offset:7344
	global_load_dword v14, v[20:21], off offset:64
	global_load_ushort v15, v[22:23], off offset:32
	s_waitcnt vmcnt(0)
	v_lshlrev_b32_e32 v15, 16, v15
	v_mul_f32_e32 v15, 0x3fd744fd, v15
	v_fmac_f32_e32 v15, v8, v14
	global_load_ushort v8, v[16:17], off offset:32
	s_waitcnt vmcnt(0)
	v_lshlrev_b32_e32 v8, 16, v8
	v_mul_f32_e32 v8, 0x3fd744fd, v8
	v_fmac_f32_e32 v8, v9, v14
	global_load_ushort v9, v[18:19], off offset:32
	v_cvt_pk_bf16_f32 v8, v8, s0
	ds_write_b16 v61, v8 offset:7088
	s_waitcnt vmcnt(0)
	v_lshlrev_b32_e32 v9, 16, v9
	v_mul_f32_e32 v9, 0x3fd744fd, v9
	v_fmac_f32_e32 v9, v10, v14
	global_load_ushort v10, v[12:13], off offset:32
	v_cvt_pk_bf16_f32 v8, v9, s0
	ds_write_b16 v61, v8 offset:7232
	s_waitcnt vmcnt(0)
	v_lshlrev_b32_e32 v10, 16, v10
	v_mul_f32_e32 v10, 0x3fd744fd, v10
	v_fmac_f32_e32 v10, v11, v14
	v_cvt_pk_bf16_f32 v11, v15, s0
	v_cvt_pk_bf16_f32 v8, v10, s0
	ds_write_b16 v61, v11 offset:6944
	ds_write_b16 v61, v8 offset:7376
	global_load_dword v8, v[20:21], off offset:128
	global_load_ushort v9, v[22:23], off offset:64
	s_waitcnt vmcnt(0)
	v_lshlrev_b32_e32 v9, 16, v9
	v_mul_f32_e32 v9, 0x3fd744fd, v9
	v_fmac_f32_e32 v9, v4, v8
	global_load_ushort v4, v[16:17], off offset:64
	s_waitcnt vmcnt(0)
	v_lshlrev_b32_e32 v4, 16, v4
	v_mul_f32_e32 v4, 0x3fd744fd, v4
	v_fmac_f32_e32 v4, v5, v8
	global_load_ushort v5, v[18:19], off offset:64
	v_cvt_pk_bf16_f32 v4, v4, s0
	ds_write_b16 v61, v4 offset:7120
	s_waitcnt vmcnt(0)
	v_lshlrev_b32_e32 v5, 16, v5
	v_mul_f32_e32 v5, 0x3fd744fd, v5
	v_fmac_f32_e32 v5, v6, v8
	global_load_ushort v6, v[12:13], off offset:64
	v_cvt_pk_bf16_f32 v4, v5, s0
	ds_write_b16 v61, v4 offset:7264
	s_waitcnt vmcnt(0)
	v_lshlrev_b32_e32 v6, 16, v6
	v_mul_f32_e32 v6, 0x3fd744fd, v6
	v_fmac_f32_e32 v6, v7, v8
	v_cvt_pk_bf16_f32 v7, v9, s0
	v_cvt_pk_bf16_f32 v4, v6, s0
	ds_write_b16 v61, v7 offset:6976
	ds_write_b16 v61, v4 offset:7408
	global_load_dword v4, v[20:21], off offset:192
	global_load_ushort v5, v[22:23], off offset:96
	s_waitcnt vmcnt(0)
	v_lshlrev_b32_e32 v5, 16, v5
	v_mul_f32_e32 v5, 0x3fd744fd, v5
	v_fmac_f32_e32 v5, v0, v4
	global_load_ushort v0, v[16:17], off offset:96
	s_waitcnt vmcnt(0)
	v_lshlrev_b32_e32 v0, 16, v0
	v_mul_f32_e32 v0, 0x3fd744fd, v0
	v_fmac_f32_e32 v0, v1, v4
	global_load_ushort v1, v[18:19], off offset:96
	v_cvt_pk_bf16_f32 v0, v0, s0
	ds_write_b16 v61, v0 offset:7152
	s_waitcnt vmcnt(0)
	v_lshlrev_b32_e32 v1, 16, v1
	v_mul_f32_e32 v1, 0x3fd744fd, v1
	v_fmac_f32_e32 v1, v2, v4
	global_load_ushort v2, v[12:13], off offset:96
	v_cvt_pk_bf16_f32 v0, v1, s0
	ds_write_b16 v61, v0 offset:7296
	v_mov_b32_e32 v1, v137
	s_waitcnt vmcnt(0)
	v_lshlrev_b32_e32 v2, 16, v2
	v_mul_f32_e32 v2, 0x3fd744fd, v2
	v_fmac_f32_e32 v2, v3, v4
	v_cvt_pk_bf16_f32 v0, v2, s0
	ds_write_b16 v61, v0 offset:7440
	v_lshlrev_b32_e32 v0, 4, v71
	v_cvt_pk_bf16_f32 v3, v5, s0
	v_and_b32_e32 v0, 0x70, v0
	ds_write_b16 v61, v3 offset:7008
	v_or_b32_e32 v6, v74, v0
	v_lshl_add_u64 v[2:3], s[4:5], 0, v[136:137]
	s_movk_i32 s4, 0x90
	v_mad_u32_u24 v10, v70, s4, v6
	v_lshl_add_u64 v[4:5], v[2:3], 0, v[0:1]
	ds_read_b128 v[0:3], v10
	v_or_b32_e32 v6, v72, v70
	v_ashrrev_i32_e32 v7, 31, v6
	v_lshlrev_b64 v[8:9], 12, v[6:7]
	v_lshl_add_u64 v[8:9], v[4:5], 0, v[8:9]
	s_waitcnt lgkmcnt(0)
	global_store_dwordx4 v[8:9], v[0:3], off offset:2048
	ds_read_b128 v[0:3], v10 offset:1152
	v_or_b32_e32 v8, 8, v6
	v_ashrrev_i32_e32 v9, 31, v8
	v_lshlrev_b64 v[8:9], 12, v[8:9]
	v_lshl_add_u64 v[8:9], v[4:5], 0, v[8:9]
	s_waitcnt lgkmcnt(0)
	global_store_dwordx4 v[8:9], v[0:3], off offset:2048
	ds_read_b128 v[0:3], v10 offset:2304
	v_or_b32_e32 v8, 16, v6
	v_ashrrev_i32_e32 v9, 31, v8
	v_lshlrev_b64 v[8:9], 12, v[8:9]
	v_lshl_add_u64 v[8:9], v[4:5], 0, v[8:9]
	s_waitcnt lgkmcnt(0)
	global_store_dwordx4 v[8:9], v[0:3], off offset:2048
	ds_read_b128 v[0:3], v10 offset:3456
	v_or_b32_e32 v8, 24, v6
	v_ashrrev_i32_e32 v9, 31, v8
	v_lshlrev_b64 v[8:9], 12, v[8:9]
	v_lshl_add_u64 v[8:9], v[4:5], 0, v[8:9]
	s_waitcnt lgkmcnt(0)
	global_store_dwordx4 v[8:9], v[0:3], off offset:2048
	ds_read_b128 v[0:3], v10 offset:4608
	v_or_b32_e32 v8, 32, v6
	v_ashrrev_i32_e32 v9, 31, v8
	v_lshlrev_b64 v[8:9], 12, v[8:9]
	v_lshl_add_u64 v[8:9], v[4:5], 0, v[8:9]
	s_waitcnt lgkmcnt(0)
	global_store_dwordx4 v[8:9], v[0:3], off offset:2048
	ds_read_b128 v[0:3], v10 offset:5760
	v_or_b32_e32 v8, 40, v6
	v_ashrrev_i32_e32 v9, 31, v8
	v_lshlrev_b64 v[8:9], 12, v[8:9]
	v_lshl_add_u64 v[8:9], v[4:5], 0, v[8:9]
	s_waitcnt lgkmcnt(0)
	global_store_dwordx4 v[8:9], v[0:3], off offset:2048
	ds_read_b128 v[0:3], v10 offset:6912
	v_or_b32_e32 v8, 48, v6
	v_ashrrev_i32_e32 v9, 31, v8
	v_lshlrev_b64 v[8:9], 12, v[8:9]
	v_lshl_add_u64 v[8:9], v[4:5], 0, v[8:9]
	s_waitcnt lgkmcnt(0)
	global_store_dwordx4 v[8:9], v[0:3], off offset:2048
	ds_read_b128 v[0:3], v10 offset:8064
	v_or_b32_e32 v6, 56, v6
	v_ashrrev_i32_e32 v7, 31, v6
	v_lshlrev_b64 v[6:7], 12, v[6:7]
	v_lshl_add_u64 v[4:5], v[4:5], 0, v[6:7]
	s_waitcnt lgkmcnt(0)
	global_store_dwordx4 v[4:5], v[0:3], off offset:2048
	s_barrier
	s_branch .LBB0_162

.LBB0_1106:
	s_and_b32 s10, s9, 0x8000
	s_xor_b32 s11, s10, 0x8000
	v_add_u32_e32 v79, s11, v74
	v_lshl_add_u64 v[80:81], v[64:65], 0, s[4:5]
	v_readfirstlane_b32 s11, v79
	v_lshl_add_u64 v[82:83], v[80:81], 0, s[28:29]
	s_mov_b32 m0, s11
	v_lshl_add_u64 v[84:85], v[66:67], 0, s[4:5]
	global_load_lds_dwordx4 v[82:83], off
	v_add_u32_e32 v82, 0x4000, v79
	v_lshl_add_u64 v[86:87], v[84:85], 0, s[28:29]
	v_readfirstlane_b32 s11, v82
	s_mov_b32 m0, s11
	v_lshl_add_u64 v[82:83], v[80:81], 0, s[12:13]
	global_load_lds_dwordx4 v[86:87], off
	v_add_u32_e32 v86, 0x1000, v79
	s_nop 0
	v_readfirstlane_b32 s11, v86
	v_add_u32_e32 v86, 0x5000, v79
	s_mov_b32 m0, s11
	v_readfirstlane_b32 s11, v86
	v_add_u32_e32 v86, 0x2000, v79
	global_load_lds_dwordx4 v[82:83], off
	v_lshl_add_u64 v[82:83], v[84:85], 0, s[12:13]
	s_mov_b32 m0, s11
	v_readfirstlane_b32 s11, v86
	v_add_u32_e32 v86, 0x6000, v79
	global_load_lds_dwordx4 v[82:83], off
	v_lshl_add_u64 v[82:83], v[80:81], 0, s[16:17]
	s_mov_b32 m0, s11
	v_readfirstlane_b32 s11, v86
	global_load_lds_dwordx4 v[82:83], off
	v_lshl_add_u64 v[82:83], v[84:85], 0, s[16:17]
	s_mov_b32 m0, s11
	v_lshl_add_u64 v[80:81], v[80:81], 0, s[14:15]
	global_load_lds_dwordx4 v[82:83], off
	v_add_u32_e32 v82, 0x3000, v79
	v_add_u32_e32 v79, 0x7000, v79
	v_readfirstlane_b32 s11, v82
	s_mov_b32 m0, s11
	v_readfirstlane_b32 s11, v79
	global_load_lds_dwordx4 v[80:81], off
	v_lshl_add_u64 v[80:81], v[84:85], 0, s[14:15]
	s_mov_b32 m0, s11
	v_or_b32_e32 v79, s10, v76
	global_load_lds_dwordx4 v[80:81], off
	v_add_u32_e32 v100, v79, v75
	v_add_u32_e32 v79, v79, v77
	ds_read_b128 v[80:83], v100
	ds_read_b128 v[84:87], v100 offset:2048
	ds_read_b128 v[88:91], v79 offset:16384
	ds_read_b128 v[92:95], v79 offset:18432
	ds_read_b128 v[96:99], v100 offset:4096
	ds_read_b128 v[100:103], v100 offset:6144
	ds_read_b128 v[104:107], v79 offset:20480
	ds_read_b128 v[108:111], v79 offset:22528
	v_or_b32_e32 v79, s10, v78
	v_add_u32_e32 v132, v79, v75
	v_add_u32_e32 v79, v79, v77
	ds_read_b128 v[112:115], v132
	ds_read_b128 v[116:119], v132 offset:2048
	ds_read_b128 v[120:123], v79 offset:16384
	ds_read_b128 v[124:127], v79 offset:18432
	ds_read_b128 v[128:131], v132 offset:4096
	ds_read_b128 v[132:135], v132 offset:6144
	ds_read_b128 v[146:149], v79 offset:20480
	ds_read_b128 v[150:153], v79 offset:22528
	s_waitcnt lgkmcnt(0)
	v_mfma_f32_16x16x32_bf16 v[60:63], v[80:83], v[88:91], v[60:63]
	v_mfma_f32_16x16x32_bf16 v[56:59], v[80:83], v[92:95], v[56:59]
	v_mfma_f32_16x16x32_bf16 v[52:55], v[80:83], v[104:107], v[52:55]
	v_mfma_f32_16x16x32_bf16 v[48:51], v[80:83], v[108:111], v[48:51]
	v_mfma_f32_16x16x32_bf16 v[44:47], v[84:87], v[88:91], v[44:47]
	v_mfma_f32_16x16x32_bf16 v[40:43], v[84:87], v[92:95], v[40:43]
	v_mfma_f32_16x16x32_bf16 v[36:39], v[84:87], v[104:107], v[36:39]
	v_mfma_f32_16x16x32_bf16 v[32:35], v[84:87], v[108:111], v[32:35]
	v_mfma_f32_16x16x32_bf16 v[28:31], v[96:99], v[88:91], v[28:31]
	v_mfma_f32_16x16x32_bf16 v[24:27], v[96:99], v[92:95], v[24:27]
	v_mfma_f32_16x16x32_bf16 v[20:23], v[96:99], v[104:107], v[20:23]
	v_mfma_f32_16x16x32_bf16 v[16:19], v[96:99], v[108:111], v[16:19]
	v_mfma_f32_16x16x32_bf16 v[12:15], v[100:103], v[88:91], v[12:15]
	v_mfma_f32_16x16x32_bf16 v[8:11], v[100:103], v[92:95], v[8:11]
	v_mfma_f32_16x16x32_bf16 v[4:7], v[100:103], v[104:107], v[4:7]
	v_mfma_f32_16x16x32_bf16 v[0:3], v[100:103], v[108:111], v[0:3]
	v_mfma_f32_16x16x32_bf16 v[60:63], v[112:115], v[120:123], v[60:63]
	v_mfma_f32_16x16x32_bf16 v[56:59], v[112:115], v[124:127], v[56:59]
	v_mfma_f32_16x16x32_bf16 v[52:55], v[112:115], v[146:149], v[52:55]
	v_mfma_f32_16x16x32_bf16 v[48:51], v[112:115], v[150:153], v[48:51]
	v_mfma_f32_16x16x32_bf16 v[44:47], v[116:119], v[120:123], v[44:47]
	v_mfma_f32_16x16x32_bf16 v[40:43], v[116:119], v[124:127], v[40:43]
	v_mfma_f32_16x16x32_bf16 v[36:39], v[116:119], v[146:149], v[36:39]
	v_mfma_f32_16x16x32_bf16 v[32:35], v[116:119], v[150:153], v[32:35]
	v_mfma_f32_16x16x32_bf16 v[28:31], v[128:131], v[120:123], v[28:31]
	v_mfma_f32_16x16x32_bf16 v[24:27], v[128:131], v[124:127], v[24:27]
	v_mfma_f32_16x16x32_bf16 v[20:23], v[128:131], v[146:149], v[20:23]
	v_mfma_f32_16x16x32_bf16 v[16:19], v[128:131], v[150:153], v[16:19]
	v_mfma_f32_16x16x32_bf16 v[12:15], v[132:135], v[120:123], v[12:15]
	v_mfma_f32_16x16x32_bf16 v[8:11], v[132:135], v[124:127], v[8:11]
	v_mfma_f32_16x16x32_bf16 v[4:7], v[132:135], v[146:149], v[4:7]
	v_mfma_f32_16x16x32_bf16 v[0:3], v[132:135], v[150:153], v[0:3]
	s_add_i32 s9, s9, 0x8000
	s_waitcnt vmcnt(0)
	s_add_u32 s4, s4, 0x80
	s_addc_u32 s5, s5, 0
	s_cmpk_lg_i32 s4, 0x780
	s_barrier
	s_cbranch_scc1 .LBB0_1106
	v_add_u32_e32 v74, v78, v77
	v_add_u32_e32 v102, v78, v75
	v_add_u32_e32 v122, v76, v77
	v_add_u32_e32 v130, v76, v75
	ds_read_b128 v[64:67], v74 offset:55296
	ds_read_b128 v[78:81], v74 offset:53248
	ds_read_b128 v[82:85], v102 offset:38912
	ds_read_b128 v[86:89], v102 offset:36864
	ds_read_b128 v[90:93], v74 offset:51200
	ds_read_b128 v[94:97], v74 offset:49152
	ds_read_b128 v[98:101], v102 offset:34816
	ds_read_b128 v[102:105], v102 offset:32768
	ds_read_b128 v[74:77], v122 offset:55296
	ds_read_b128 v[106:109], v122 offset:53248
	ds_read_b128 v[110:113], v130 offset:38912
	ds_read_b128 v[114:117], v130 offset:36864
	ds_read_b128 v[118:121], v122 offset:51200
	ds_read_b128 v[122:125], v122 offset:49152
	ds_read_b128 v[126:129], v130 offset:34816
	ds_read_b128 v[130:133], v130 offset:32768
	v_and_b32_e32 v134, 64, v69
	s_waitcnt lgkmcnt(0)
	v_mfma_f32_16x16x32_bf16 v[60:63], v[130:133], v[122:125], v[60:63]
	v_mfma_f32_16x16x32_bf16 v[56:59], v[130:133], v[118:121], v[56:59]
	v_mfma_f32_16x16x32_bf16 v[52:55], v[130:133], v[106:109], v[52:55]
	v_mfma_f32_16x16x32_bf16 v[48:51], v[130:133], v[74:77], v[48:51]
	v_mfma_f32_16x16x32_bf16 v[44:47], v[126:129], v[122:125], v[44:47]
	v_mfma_f32_16x16x32_bf16 v[40:43], v[126:129], v[118:121], v[40:43]
	v_mfma_f32_16x16x32_bf16 v[36:39], v[126:129], v[106:109], v[36:39]
	v_mfma_f32_16x16x32_bf16 v[32:35], v[126:129], v[74:77], v[32:35]
	v_mfma_f32_16x16x32_bf16 v[28:31], v[114:117], v[122:125], v[28:31]
	v_mfma_f32_16x16x32_bf16 v[24:27], v[114:117], v[118:121], v[24:27]
	v_mfma_f32_16x16x32_bf16 v[20:23], v[114:117], v[106:109], v[20:23]
	v_mfma_f32_16x16x32_bf16 v[16:19], v[114:117], v[74:77], v[16:19]
	v_mfma_f32_16x16x32_bf16 v[12:15], v[110:113], v[122:125], v[12:15]
	v_mfma_f32_16x16x32_bf16 v[8:11], v[110:113], v[118:121], v[8:11]
	v_mfma_f32_16x16x32_bf16 v[4:7], v[110:113], v[106:109], v[4:7]
	v_mfma_f32_16x16x32_bf16 v[0:3], v[110:113], v[74:77], v[0:3]
	v_mfma_f32_16x16x32_bf16 v[60:63], v[102:105], v[94:97], v[60:63]
	v_mfma_f32_16x16x32_bf16 v[56:59], v[102:105], v[90:93], v[56:59]
	v_mfma_f32_16x16x32_bf16 v[52:55], v[102:105], v[78:81], v[52:55]
	v_mfma_f32_16x16x32_bf16 v[48:51], v[102:105], v[64:67], v[48:51]
	v_mfma_f32_16x16x32_bf16 v[44:47], v[98:101], v[94:97], v[44:47]
	v_mfma_f32_16x16x32_bf16 v[40:43], v[98:101], v[90:93], v[40:43]
	v_mfma_f32_16x16x32_bf16 v[36:39], v[98:101], v[78:81], v[36:39]
	v_mfma_f32_16x16x32_bf16 v[32:35], v[98:101], v[64:67], v[32:35]
	v_mfma_f32_16x16x32_bf16 v[28:31], v[86:89], v[94:97], v[28:31]
	v_mfma_f32_16x16x32_bf16 v[24:27], v[86:89], v[90:93], v[24:27]
	v_mfma_f32_16x16x32_bf16 v[20:23], v[86:89], v[78:81], v[20:23]
	v_mfma_f32_16x16x32_bf16 v[16:19], v[86:89], v[64:67], v[16:19]
	v_mfma_f32_16x16x32_bf16 v[12:15], v[82:85], v[94:97], v[12:15]
	v_mfma_f32_16x16x32_bf16 v[8:11], v[82:85], v[90:93], v[8:11]
	v_mfma_f32_16x16x32_bf16 v[4:7], v[82:85], v[78:81], v[4:7]
	v_mfma_f32_16x16x32_bf16 v[0:3], v[82:85], v[64:67], v[0:3]
	s_movk_i32 s4, 0x2400
	v_mul_lo_u32 v64, v72, s4
	v_lshl_or_b32 v65, v73, 1, v64
	s_movk_i32 s4, 0x240
	v_cvt_pk_bf16_f32 v60, v60, s0
	v_mad_u32_u24 v65, v71, s4, v65
	v_cvt_pk_bf16_f32 v56, v56, s0
	v_cvt_pk_bf16_f32 v52, v52, s0
	v_cvt_pk_bf16_f32 v48, v48, s0
	v_cvt_pk_bf16_f32 v44, v44, s0
	v_cvt_pk_bf16_f32 v40, v40, s0
	v_cvt_pk_bf16_f32 v36, v36, s0
	v_cvt_pk_bf16_f32 v32, v32, s0
	v_cvt_pk_bf16_f32 v28, v28, s0
	v_cvt_pk_bf16_f32 v24, v24, s0
	v_cvt_pk_bf16_f32 v20, v20, s0
	v_cvt_pk_bf16_f32 v16, v16, s0
	v_cvt_pk_bf16_f32 v12, v12, s0
	v_cvt_pk_bf16_f32 v8, v8, s0
	v_cvt_pk_bf16_f32 v4, v4, s0
	v_cvt_pk_bf16_f32 v0, v0, s0
	s_waitcnt vmcnt(0)
	s_barrier
	ds_write_b16 v65, v60
	v_cvt_pk_bf16_f32 v60, v61, s0
	ds_write_b16 v65, v56 offset:32
	v_cvt_pk_bf16_f32 v56, v57, s0
	ds_write_b16 v65, v52 offset:64
	v_cvt_pk_bf16_f32 v52, v53, s0
	ds_write_b16 v65, v48 offset:96
	v_cvt_pk_bf16_f32 v48, v49, s0
	ds_write_b16 v65, v44 offset:2304
	v_cvt_pk_bf16_f32 v44, v45, s0
	ds_write_b16 v65, v40 offset:2336
	v_cvt_pk_bf16_f32 v40, v41, s0
	ds_write_b16 v65, v36 offset:2368
	v_cvt_pk_bf16_f32 v36, v37, s0
	ds_write_b16 v65, v32 offset:2400
	v_cvt_pk_bf16_f32 v32, v33, s0
	ds_write_b16 v65, v28 offset:4608
	v_cvt_pk_bf16_f32 v28, v29, s0
	ds_write_b16 v65, v24 offset:4640
	v_cvt_pk_bf16_f32 v24, v25, s0
	ds_write_b16 v65, v20 offset:4672
	v_cvt_pk_bf16_f32 v20, v21, s0
	ds_write_b16 v65, v16 offset:4704
	v_cvt_pk_bf16_f32 v16, v17, s0
	ds_write_b16 v65, v12 offset:6912
	v_cvt_pk_bf16_f32 v12, v13, s0
	ds_write_b16 v65, v8 offset:6944
	v_cvt_pk_bf16_f32 v8, v9, s0
	ds_write_b16 v65, v4 offset:6976
	v_cvt_pk_bf16_f32 v4, v5, s0
	ds_write_b16 v65, v0 offset:7008
	v_cvt_pk_bf16_f32 v0, v1, s0
	ds_write_b16 v65, v60 offset:144
	v_cvt_pk_bf16_f32 v60, v62, s0
	ds_write_b16 v65, v56 offset:176
	v_cvt_pk_bf16_f32 v56, v58, s0
	ds_write_b16 v65, v52 offset:208
	v_cvt_pk_bf16_f32 v52, v54, s0
	ds_write_b16 v65, v48 offset:240
	v_cvt_pk_bf16_f32 v48, v50, s0
	ds_write_b16 v65, v44 offset:2448
	v_cvt_pk_bf16_f32 v44, v46, s0
	ds_write_b16 v65, v40 offset:2480
	v_cvt_pk_bf16_f32 v40, v42, s0
	ds_write_b16 v65, v36 offset:2512
	v_cvt_pk_bf16_f32 v36, v38, s0
	ds_write_b16 v65, v32 offset:2544
	v_cvt_pk_bf16_f32 v32, v34, s0
	ds_write_b16 v65, v28 offset:4752
	v_cvt_pk_bf16_f32 v28, v30, s0
	ds_write_b16 v65, v24 offset:4784
	v_cvt_pk_bf16_f32 v24, v26, s0
	ds_write_b16 v65, v20 offset:4816
	v_cvt_pk_bf16_f32 v20, v22, s0
	ds_write_b16 v65, v16 offset:4848
	v_cvt_pk_bf16_f32 v16, v18, s0
	ds_write_b16 v65, v12 offset:7056
	v_cvt_pk_bf16_f32 v12, v14, s0
	ds_write_b16 v65, v8 offset:7088
	v_cvt_pk_bf16_f32 v8, v10, s0
	ds_write_b16 v65, v4 offset:7120
	v_cvt_pk_bf16_f32 v4, v6, s0
	ds_write_b16 v65, v0 offset:7152
	v_cvt_pk_bf16_f32 v0, v2, s0
	v_add_u32_e32 v5, s1, v70
	s_ashr_i32 s1, s0, 31
	ds_write_b16 v65, v60 offset:288
	v_cvt_pk_bf16_f32 v60, v63, s0
	ds_write_b16 v65, v56 offset:320
	v_cvt_pk_bf16_f32 v56, v59, s0
	ds_write_b16 v65, v52 offset:352
	v_cvt_pk_bf16_f32 v52, v55, s0
	ds_write_b16 v65, v48 offset:384
	v_cvt_pk_bf16_f32 v48, v51, s0
	ds_write_b16 v65, v44 offset:2592
	v_cvt_pk_bf16_f32 v44, v47, s0
	ds_write_b16 v65, v40 offset:2624
	v_cvt_pk_bf16_f32 v40, v43, s0
	ds_write_b16 v65, v36 offset:2656
	v_cvt_pk_bf16_f32 v36, v39, s0
	ds_write_b16 v65, v32 offset:2688
	v_cvt_pk_bf16_f32 v32, v35, s0
	ds_write_b16 v65, v28 offset:4896
	v_cvt_pk_bf16_f32 v28, v31, s0
	ds_write_b16 v65, v24 offset:4928
	v_cvt_pk_bf16_f32 v24, v27, s0
	ds_write_b16 v65, v20 offset:4960
	v_cvt_pk_bf16_f32 v20, v23, s0
	ds_write_b16 v65, v16 offset:4992
	v_cvt_pk_bf16_f32 v16, v19, s0
	ds_write_b16 v65, v12 offset:7200
	v_cvt_pk_bf16_f32 v12, v15, s0
	ds_write_b16 v65, v8 offset:7232
	v_cvt_pk_bf16_f32 v8, v11, s0
	ds_write_b16 v65, v4 offset:7264
	v_cvt_pk_bf16_f32 v4, v7, s0
	ds_write_b16 v65, v0 offset:7296
	v_cvt_pk_bf16_f32 v0, v3, s0
	s_lshl_b64 s[0:1], s[0:1], 1
	v_readlane_b32 s36, v246, 25
	ds_write_b16 v65, v0 offset:7440
	v_lshlrev_b32_e32 v0, 4, v69
	v_readlane_b32 s37, v246, 26
	s_add_u32 s0, s36, s0
	v_and_b32_e32 v0, 0x70, v0
	s_addc_u32 s1, s37, s1
	v_lshlrev_b32_e32 v136, 1, v134
	ds_write_b16 v65, v4 offset:7408
	v_or_b32_e32 v4, v64, v0
	v_lshl_add_u64 v[2:3], s[0:1], 0, v[136:137]
	s_movk_i32 s0, 0x90
	ds_write_b16 v65, v60 offset:432
	ds_write_b16 v65, v56 offset:464
	ds_write_b16 v65, v52 offset:496
	ds_write_b16 v65, v48 offset:528
	ds_write_b16 v65, v44 offset:2736
	ds_write_b16 v65, v40 offset:2768
	ds_write_b16 v65, v36 offset:2800
	ds_write_b16 v65, v32 offset:2832
	ds_write_b16 v65, v28 offset:5040
	ds_write_b16 v65, v24 offset:5072
	ds_write_b16 v65, v20 offset:5104
	ds_write_b16 v65, v16 offset:5136
	ds_write_b16 v65, v12 offset:7344
	ds_write_b16 v65, v8 offset:7376
	v_mov_b32_e32 v1, v137
	v_mad_u32_u24 v12, v68, s0, v4
	v_lshl_add_u64 v[8:9], v[2:3], 0, v[0:1]
	ds_read_b128 v[0:3], v12
	v_or_b32_e32 v13, v5, v68
	ds_read_b128 v[4:7], v12 offset:1152
	s_movk_i32 s4, 0x1a00
	v_mad_i64_i32 v[10:11], s[0:1], v13, s4, v[8:9]
	s_waitcnt lgkmcnt(1)
	global_store_dwordx4 v[10:11], v[0:3], off
	s_add_i32 s6, s6, 1
	s_movk_i32 s36, 0x880
	v_or_b32_e32 v0, 8, v13
	v_mad_i64_i32 v[0:1], s[0:1], v0, s4, v[8:9]
	s_waitcnt lgkmcnt(0)
	global_store_dwordx4 v[0:1], v[4:7], off
	ds_read_b128 v[0:3], v12 offset:2304
	v_readlane_b32 s38, v246, 27
	v_or_b32_e32 v4, 16, v13
	v_mad_i64_i32 v[10:11], s[0:1], v4, s4, v[8:9]
	ds_read_b128 v[4:7], v12 offset:3456
	s_waitcnt lgkmcnt(1)
	global_store_dwordx4 v[10:11], v[0:3], off
	v_readlane_b32 s39, v246, 28
	v_readlane_b32 s40, v246, 29
	v_or_b32_e32 v0, 24, v13
	v_mad_i64_i32 v[0:1], s[0:1], v0, s4, v[8:9]
	s_waitcnt lgkmcnt(0)
	global_store_dwordx4 v[0:1], v[4:7], off
	ds_read_b128 v[0:3], v12 offset:4608
	v_readlane_b32 s41, v246, 30
	v_or_b32_e32 v4, 32, v13
	v_mad_i64_i32 v[10:11], s[0:1], v4, s4, v[8:9]
	ds_read_b128 v[4:7], v12 offset:5760
	s_waitcnt lgkmcnt(1)
	global_store_dwordx4 v[10:11], v[0:3], off
	v_readlane_b32 s42, v246, 31
	v_readlane_b32 s43, v246, 32
	v_or_b32_e32 v0, 40, v13
	v_mad_i64_i32 v[0:1], s[0:1], v0, s4, v[8:9]
	s_waitcnt lgkmcnt(0)
	global_store_dwordx4 v[0:1], v[4:7], off
	ds_read_b128 v[0:3], v12 offset:6912
	v_readlane_b32 s44, v246, 33
	v_or_b32_e32 v4, 48, v13
	v_mad_i64_i32 v[10:11], s[0:1], v4, s4, v[8:9]
	ds_read_b128 v[4:7], v12 offset:8064
	s_waitcnt lgkmcnt(1)
	global_store_dwordx4 v[10:11], v[0:3], off
	v_readlane_b32 s45, v246, 34
	v_readlane_b32 s46, v246, 35
	v_or_b32_e32 v0, 56, v13
	v_mad_i64_i32 v[0:1], s[0:1], v0, s4, v[8:9]
	s_mov_b64 s[0:1], 0
	v_readlane_b32 s47, v246, 36
	v_readlane_b32 s48, v246, 37
	v_readlane_b32 s49, v246, 38
	v_readlane_b32 s50, v246, 39
	v_readlane_b32 s51, v246, 40
	s_waitcnt lgkmcnt(0)
	global_store_dwordx4 v[0:1], v[4:7], off
	s_barrier
	s_branch .LBB0_1095
